# FRes epilogue: four loads of a block issued together with counted vmcnt waits; LR2/RGG per-item bias hoist without per-section waits; 8-step scan combine
# speedup vs baseline: 1.0854x; 1.0106x over previous
.LBB0_104:
	s_or_b64 exec, exec, s[60:61]
	s_and_saveexec_b64 s[60:61], s[58:59]
	s_cbranch_execz .LBB0_106
	global_load_dwordx4 v[168:171], v[144:145], off
	global_load_dwordx4 v[184:187], v[166:167], off
	global_load_dwordx4 v[194:197], v[144:145], off offset:64
	global_load_dwordx4 v[198:201], v[166:167], off offset:64
	s_waitcnt vmcnt(2)
	v_pk_fma_f32 v[170:171], v[126:127], v[186:187], v[170:171]
	v_pk_fma_f32 v[168:169], v[124:125], v[184:185], v[168:169]
	global_store_dwordx4 v[140:141], v[168:171], off
	s_waitcnt vmcnt(1)
	v_pk_fma_f32 v[196:197], v[122:123], v[200:201], v[196:197]
	v_pk_fma_f32 v[194:195], v[120:121], v[198:199], v[194:195]
	global_store_dwordx4 v[140:141], v[194:197], off offset:64

.LBB0_148:
	global_load_dwordx4 v[170:173], v[138:139], off
	global_load_dwordx4 v[186:189], v[168:169], off
	global_load_dwordx4 v[194:197], v[138:139], off offset:64
	global_load_dwordx4 v[198:201], v[168:169], off offset:64
	s_waitcnt vmcnt(2)
	v_pk_fma_f32 v[172:173], v[126:127], v[188:189], v[172:173]
	v_pk_fma_f32 v[170:171], v[124:125], v[186:187], v[170:171]
	global_store_dwordx4 v[138:139], v[170:173], off
	s_waitcnt vmcnt(1)
	v_pk_fma_f32 v[196:197], v[122:123], v[200:201], v[196:197]
	v_pk_fma_f32 v[194:195], v[120:121], v[198:199], v[194:195]
	global_store_dwordx4 v[138:139], v[194:197], off offset:64

.LBB0_165:
	global_load_dwordx4 v[146:149], v[124:125], off
	global_load_dwordx4 v[170:173], v[126:127], off
	global_load_dwordx4 v[194:197], v[124:125], off offset:64
	global_load_dwordx4 v[198:201], v[126:127], off offset:64
	s_waitcnt vmcnt(2)
	v_pk_fma_f32 v[148:149], v[118:119], v[172:173], v[148:149]
	v_pk_fma_f32 v[146:147], v[116:117], v[170:171], v[146:147]
	global_store_dwordx4 v[122:123], v[146:149], off
	s_waitcnt vmcnt(1)
	v_pk_fma_f32 v[196:197], v[114:115], v[200:201], v[196:197]
	v_pk_fma_f32 v[194:195], v[112:113], v[198:199], v[194:195]
	global_store_dwordx4 v[122:123], v[194:197], off offset:64

.LBB0_207:
	global_load_dwordx4 v[142:145], v[122:123], off
	global_load_dwordx4 v[146:149], v[124:125], off
	global_load_dwordx4 v[194:197], v[122:123], off offset:64
	global_load_dwordx4 v[198:201], v[124:125], off offset:64
	s_waitcnt vmcnt(2)
	v_pk_fma_f32 v[144:145], v[118:119], v[148:149], v[144:145]
	v_pk_fma_f32 v[142:143], v[116:117], v[146:147], v[142:143]
	global_store_dwordx4 v[122:123], v[142:145], off
	s_waitcnt vmcnt(1)
	v_pk_fma_f32 v[196:197], v[114:115], v[200:201], v[196:197]
	v_pk_fma_f32 v[194:195], v[112:113], v[198:199], v[194:195]
	global_store_dwordx4 v[122:123], v[194:197], off offset:64

.LBB0_224:
	global_load_dwordx4 v[144:147], v[116:117], off
	global_load_dwordx4 v[170:173], v[142:143], off
	global_load_dwordx4 v[194:197], v[116:117], off offset:64
	global_load_dwordx4 v[198:201], v[142:143], off offset:64
	s_waitcnt vmcnt(2)
	v_pk_fma_f32 v[146:147], v[110:111], v[172:173], v[146:147]
	v_pk_fma_f32 v[144:145], v[108:109], v[170:171], v[144:145]
	global_store_dwordx4 v[112:113], v[144:147], off
	s_waitcnt vmcnt(1)
	v_pk_fma_f32 v[196:197], v[106:107], v[200:201], v[196:197]
	v_pk_fma_f32 v[194:195], v[104:105], v[198:199], v[194:195]
	global_store_dwordx4 v[112:113], v[194:197], off offset:64

.LBB0_266:
	global_load_dwordx4 v[146:149], v[142:143], off
	global_load_dwordx4 v[170:173], v[144:145], off
	global_load_dwordx4 v[194:197], v[142:143], off offset:64
	global_load_dwordx4 v[198:201], v[144:145], off offset:64
	s_waitcnt vmcnt(2)
	v_pk_fma_f32 v[148:149], v[110:111], v[172:173], v[148:149]
	v_pk_fma_f32 v[146:147], v[108:109], v[170:171], v[146:147]
	global_store_dwordx4 v[142:143], v[146:149], off
	s_waitcnt vmcnt(1)
	v_pk_fma_f32 v[196:197], v[106:107], v[200:201], v[196:197]
	v_pk_fma_f32 v[194:195], v[104:105], v[198:199], v[194:195]
	global_store_dwordx4 v[142:143], v[194:197], off offset:64

.LBB0_283:
	global_load_dwordx4 v[142:145], v[106:107], off
	global_load_dwordx4 v[146:149], v[108:109], off
	global_load_dwordx4 v[194:197], v[106:107], off offset:64
	global_load_dwordx4 v[198:201], v[108:109], off offset:64
	s_waitcnt vmcnt(2)
	v_pk_fma_f32 v[144:145], v[102:103], v[148:149], v[144:145]
	v_pk_fma_f32 v[142:143], v[100:101], v[146:147], v[142:143]
	global_store_dwordx4 v[104:105], v[142:145], off
	s_waitcnt vmcnt(1)
	v_pk_fma_f32 v[196:197], v[98:99], v[200:201], v[196:197]
	v_pk_fma_f32 v[194:195], v[96:97], v[198:199], v[194:195]
	global_store_dwordx4 v[104:105], v[194:197], off offset:64

.LBB0_325:
	global_load_dwordx4 v[108:111], v[104:105], off
	global_load_dwordx4 v[114:117], v[106:107], off
	global_load_dwordx4 v[194:197], v[104:105], off offset:64
	global_load_dwordx4 v[198:201], v[106:107], off offset:64
	s_waitcnt vmcnt(2)
	v_pk_fma_f32 v[110:111], v[102:103], v[116:117], v[110:111]
	v_pk_fma_f32 v[108:109], v[100:101], v[114:115], v[108:109]
	global_store_dwordx4 v[104:105], v[108:111], off
	s_waitcnt vmcnt(1)
	v_pk_fma_f32 v[196:197], v[98:99], v[200:201], v[196:197]
	v_pk_fma_f32 v[194:195], v[96:97], v[198:199], v[194:195]
	global_store_dwordx4 v[104:105], v[194:197], off offset:64

.LBB0_342:
	global_load_dwordx4 v[112:115], v[100:101], off
	global_load_dwordx4 v[116:119], v[110:111], off
	global_load_dwordx4 v[194:197], v[100:101], off offset:64
	global_load_dwordx4 v[198:201], v[110:111], off offset:64
	s_waitcnt vmcnt(2)
	v_pk_fma_f32 v[114:115], v[94:95], v[118:119], v[114:115]
	v_pk_fma_f32 v[112:113], v[92:93], v[116:117], v[112:113]
	global_store_dwordx4 v[96:97], v[112:115], off
	s_waitcnt vmcnt(1)
	v_pk_fma_f32 v[196:197], v[90:91], v[200:201], v[196:197]
	v_pk_fma_f32 v[194:195], v[88:89], v[198:199], v[194:195]
	global_store_dwordx4 v[96:97], v[194:197], off offset:64

.LBB0_384:
	global_load_dwordx4 v[114:117], v[110:111], off
	global_load_dwordx4 v[124:127], v[112:113], off
	global_load_dwordx4 v[194:197], v[110:111], off offset:64
	global_load_dwordx4 v[198:201], v[112:113], off offset:64
	s_waitcnt vmcnt(2)
	v_pk_fma_f32 v[116:117], v[94:95], v[126:127], v[116:117]
	v_pk_fma_f32 v[114:115], v[92:93], v[124:125], v[114:115]
	global_store_dwordx4 v[110:111], v[114:117], off
	s_waitcnt vmcnt(1)
	v_pk_fma_f32 v[196:197], v[90:91], v[200:201], v[196:197]
	v_pk_fma_f32 v[194:195], v[88:89], v[198:199], v[194:195]
	global_store_dwordx4 v[110:111], v[194:197], off offset:64

.LBB0_401:
	global_load_dwordx4 v[102:105], v[90:91], off
	global_load_dwordx4 v[110:113], v[92:93], off
	global_load_dwordx4 v[194:197], v[90:91], off offset:64
	global_load_dwordx4 v[198:201], v[92:93], off offset:64
	s_waitcnt vmcnt(2)
	v_pk_fma_f32 v[104:105], v[86:87], v[112:113], v[104:105]
	v_pk_fma_f32 v[102:103], v[84:85], v[110:111], v[102:103]
	global_store_dwordx4 v[88:89], v[102:105], off
	s_waitcnt vmcnt(1)
	v_pk_fma_f32 v[196:197], v[82:83], v[200:201], v[196:197]
	v_pk_fma_f32 v[194:195], v[80:81], v[198:199], v[194:195]
	global_store_dwordx4 v[88:89], v[194:197], off offset:64

.LBB0_443:
	global_load_dwordx4 v[92:95], v[88:89], off
	global_load_dwordx4 v[98:101], v[90:91], off
	global_load_dwordx4 v[194:197], v[88:89], off offset:64
	global_load_dwordx4 v[198:201], v[90:91], off offset:64
	s_waitcnt vmcnt(2)
	v_pk_fma_f32 v[94:95], v[86:87], v[100:101], v[94:95]
	v_pk_fma_f32 v[92:93], v[84:85], v[98:99], v[92:93]
	global_store_dwordx4 v[88:89], v[92:95], off
	s_waitcnt vmcnt(1)
	v_pk_fma_f32 v[196:197], v[82:83], v[200:201], v[196:197]
	v_pk_fma_f32 v[194:195], v[80:81], v[198:199], v[194:195]
	global_store_dwordx4 v[88:89], v[194:197], off offset:64

.LBB0_460:
	global_load_dwordx4 v[96:99], v[84:85], off
	global_load_dwordx4 v[100:103], v[94:95], off
	global_load_dwordx4 v[194:197], v[84:85], off offset:64
	global_load_dwordx4 v[198:201], v[94:95], off offset:64
	s_waitcnt vmcnt(2)
	v_pk_fma_f32 v[98:99], v[78:79], v[102:103], v[98:99]
	v_pk_fma_f32 v[96:97], v[76:77], v[100:101], v[96:97]
	global_store_dwordx4 v[80:81], v[96:99], off
	s_waitcnt vmcnt(1)
	v_pk_fma_f32 v[196:197], v[74:75], v[200:201], v[196:197]
	v_pk_fma_f32 v[194:195], v[72:73], v[198:199], v[194:195]
	global_store_dwordx4 v[80:81], v[194:197], off offset:64

.LBB0_502:
	global_load_dwordx4 v[98:101], v[94:95], off
	global_load_dwordx4 v[104:107], v[96:97], off
	global_load_dwordx4 v[194:197], v[94:95], off offset:64
	global_load_dwordx4 v[198:201], v[96:97], off offset:64
	s_waitcnt vmcnt(2)
	v_pk_fma_f32 v[100:101], v[78:79], v[106:107], v[100:101]
	v_pk_fma_f32 v[98:99], v[76:77], v[104:105], v[98:99]
	global_store_dwordx4 v[94:95], v[98:101], off
	s_waitcnt vmcnt(1)
	v_pk_fma_f32 v[196:197], v[74:75], v[200:201], v[196:197]
	v_pk_fma_f32 v[194:195], v[72:73], v[198:199], v[194:195]
	global_store_dwordx4 v[94:95], v[194:197], off offset:64

.LBB0_519:
	global_load_dwordx4 v[86:89], v[74:75], off
	global_load_dwordx4 v[94:97], v[76:77], off
	global_load_dwordx4 v[194:197], v[74:75], off offset:64
	global_load_dwordx4 v[198:201], v[76:77], off offset:64
	s_waitcnt vmcnt(2)
	v_pk_fma_f32 v[88:89], v[70:71], v[96:97], v[88:89]
	v_pk_fma_f32 v[86:87], v[68:69], v[94:95], v[86:87]
	global_store_dwordx4 v[72:73], v[86:89], off
	s_waitcnt vmcnt(1)
	v_pk_fma_f32 v[196:197], v[66:67], v[200:201], v[196:197]
	v_pk_fma_f32 v[194:195], v[64:65], v[198:199], v[194:195]
	global_store_dwordx4 v[72:73], v[194:197], off offset:64

.LBB0_561:
	global_load_dwordx4 v[76:79], v[72:73], off
	global_load_dwordx4 v[82:85], v[74:75], off
	global_load_dwordx4 v[194:197], v[72:73], off offset:64
	global_load_dwordx4 v[198:201], v[74:75], off offset:64
	s_waitcnt vmcnt(2)
	v_pk_fma_f32 v[78:79], v[70:71], v[84:85], v[78:79]
	v_pk_fma_f32 v[76:77], v[68:69], v[82:83], v[76:77]
	global_store_dwordx4 v[72:73], v[76:79], off
	s_waitcnt vmcnt(1)
	v_pk_fma_f32 v[196:197], v[66:67], v[200:201], v[196:197]
	v_pk_fma_f32 v[194:195], v[64:65], v[198:199], v[194:195]
	global_store_dwordx4 v[72:73], v[194:197], off offset:64

.LBB0_578:
	global_load_dwordx4 v[80:83], v[68:69], off
	global_load_dwordx4 v[84:87], v[78:79], off
	global_load_dwordx4 v[194:197], v[68:69], off offset:64
	global_load_dwordx4 v[198:201], v[78:79], off offset:64
	s_waitcnt vmcnt(2)
	v_pk_fma_f32 v[82:83], v[62:63], v[86:87], v[82:83]
	v_pk_fma_f32 v[80:81], v[60:61], v[84:85], v[80:81]
	global_store_dwordx4 v[64:65], v[80:83], off
	s_waitcnt vmcnt(1)
	v_pk_fma_f32 v[196:197], v[58:59], v[200:201], v[196:197]
	v_pk_fma_f32 v[194:195], v[56:57], v[198:199], v[194:195]
	global_store_dwordx4 v[64:65], v[194:197], off offset:64

.LBB0_620:
	global_load_dwordx4 v[82:85], v[78:79], off
	global_load_dwordx4 v[88:91], v[80:81], off
	global_load_dwordx4 v[194:197], v[78:79], off offset:64
	global_load_dwordx4 v[198:201], v[80:81], off offset:64
	s_waitcnt vmcnt(2)
	v_pk_fma_f32 v[84:85], v[62:63], v[90:91], v[84:85]
	v_pk_fma_f32 v[82:83], v[60:61], v[88:89], v[82:83]
	global_store_dwordx4 v[78:79], v[82:85], off
	s_waitcnt vmcnt(1)
	v_pk_fma_f32 v[196:197], v[58:59], v[200:201], v[196:197]
	v_pk_fma_f32 v[194:195], v[56:57], v[198:199], v[194:195]
	global_store_dwordx4 v[78:79], v[194:197], off offset:64

.LBB0_637:
	global_load_dwordx4 v[70:73], v[58:59], off
	global_load_dwordx4 v[78:81], v[60:61], off
	global_load_dwordx4 v[194:197], v[58:59], off offset:64
	global_load_dwordx4 v[198:201], v[60:61], off offset:64
	s_waitcnt vmcnt(2)
	v_pk_fma_f32 v[72:73], v[54:55], v[80:81], v[72:73]
	v_pk_fma_f32 v[70:71], v[52:53], v[78:79], v[70:71]
	global_store_dwordx4 v[56:57], v[70:73], off
	s_waitcnt vmcnt(1)
	v_pk_fma_f32 v[196:197], v[50:51], v[200:201], v[196:197]
	v_pk_fma_f32 v[194:195], v[48:49], v[198:199], v[194:195]
	global_store_dwordx4 v[56:57], v[194:197], off offset:64

.LBB0_679:
	global_load_dwordx4 v[60:63], v[56:57], off
	global_load_dwordx4 v[66:69], v[58:59], off
	global_load_dwordx4 v[194:197], v[56:57], off offset:64
	global_load_dwordx4 v[198:201], v[58:59], off offset:64
	s_waitcnt vmcnt(2)
	v_pk_fma_f32 v[62:63], v[54:55], v[68:69], v[62:63]
	v_pk_fma_f32 v[60:61], v[52:53], v[66:67], v[60:61]
	global_store_dwordx4 v[56:57], v[60:63], off
	s_waitcnt vmcnt(1)
	v_pk_fma_f32 v[196:197], v[50:51], v[200:201], v[196:197]
	v_pk_fma_f32 v[194:195], v[48:49], v[198:199], v[194:195]
	global_store_dwordx4 v[56:57], v[194:197], off offset:64

.LBB0_696:
	global_load_dwordx4 v[64:67], v[52:53], off
	global_load_dwordx4 v[68:71], v[62:63], off
	global_load_dwordx4 v[194:197], v[52:53], off offset:64
	global_load_dwordx4 v[198:201], v[62:63], off offset:64
	s_waitcnt vmcnt(2)
	v_pk_fma_f32 v[66:67], v[46:47], v[70:71], v[66:67]
	v_pk_fma_f32 v[64:65], v[44:45], v[68:69], v[64:65]
	global_store_dwordx4 v[48:49], v[64:67], off
	s_waitcnt vmcnt(1)
	v_pk_fma_f32 v[196:197], v[42:43], v[200:201], v[196:197]
	v_pk_fma_f32 v[194:195], v[40:41], v[198:199], v[194:195]
	global_store_dwordx4 v[48:49], v[194:197], off offset:64

.LBB0_738:
	global_load_dwordx4 v[66:69], v[62:63], off
	global_load_dwordx4 v[72:75], v[64:65], off
	global_load_dwordx4 v[194:197], v[62:63], off offset:64
	global_load_dwordx4 v[198:201], v[64:65], off offset:64
	s_waitcnt vmcnt(2)
	v_pk_fma_f32 v[68:69], v[46:47], v[74:75], v[68:69]
	v_pk_fma_f32 v[66:67], v[44:45], v[72:73], v[66:67]
	global_store_dwordx4 v[62:63], v[66:69], off
	s_waitcnt vmcnt(1)
	v_pk_fma_f32 v[196:197], v[42:43], v[200:201], v[196:197]
	v_pk_fma_f32 v[194:195], v[40:41], v[198:199], v[194:195]
	global_store_dwordx4 v[62:63], v[194:197], off offset:64

.LBB0_755:
	global_load_dwordx4 v[54:57], v[42:43], off
	global_load_dwordx4 v[62:65], v[44:45], off
	global_load_dwordx4 v[194:197], v[42:43], off offset:64
	global_load_dwordx4 v[198:201], v[44:45], off offset:64
	s_waitcnt vmcnt(2)
	v_pk_fma_f32 v[56:57], v[38:39], v[64:65], v[56:57]
	v_pk_fma_f32 v[54:55], v[36:37], v[62:63], v[54:55]
	global_store_dwordx4 v[40:41], v[54:57], off
	s_waitcnt vmcnt(1)
	v_pk_fma_f32 v[196:197], v[34:35], v[200:201], v[196:197]
	v_pk_fma_f32 v[194:195], v[32:33], v[198:199], v[194:195]
	global_store_dwordx4 v[40:41], v[194:197], off offset:64

.LBB0_797:
	global_load_dwordx4 v[44:47], v[40:41], off
	global_load_dwordx4 v[50:53], v[42:43], off
	global_load_dwordx4 v[194:197], v[40:41], off offset:64
	global_load_dwordx4 v[198:201], v[42:43], off offset:64
	s_waitcnt vmcnt(2)
	v_pk_fma_f32 v[46:47], v[38:39], v[52:53], v[46:47]
	v_pk_fma_f32 v[44:45], v[36:37], v[50:51], v[44:45]
	global_store_dwordx4 v[40:41], v[44:47], off
	s_waitcnt vmcnt(1)
	v_pk_fma_f32 v[196:197], v[34:35], v[200:201], v[196:197]
	v_pk_fma_f32 v[194:195], v[32:33], v[198:199], v[194:195]
	global_store_dwordx4 v[40:41], v[194:197], off offset:64

.LBB0_814:
	global_load_dwordx4 v[48:51], v[36:37], off
	global_load_dwordx4 v[52:55], v[46:47], off
	global_load_dwordx4 v[194:197], v[36:37], off offset:64
	global_load_dwordx4 v[198:201], v[46:47], off offset:64
	s_waitcnt vmcnt(2)
	v_pk_fma_f32 v[50:51], v[30:31], v[54:55], v[50:51]
	v_pk_fma_f32 v[48:49], v[28:29], v[52:53], v[48:49]
	global_store_dwordx4 v[32:33], v[48:51], off
	s_waitcnt vmcnt(1)
	v_pk_fma_f32 v[196:197], v[26:27], v[200:201], v[196:197]
	v_pk_fma_f32 v[194:195], v[24:25], v[198:199], v[194:195]
	global_store_dwordx4 v[32:33], v[194:197], off offset:64

.LBB0_856:
	global_load_dwordx4 v[50:53], v[46:47], off
	global_load_dwordx4 v[56:59], v[48:49], off
	global_load_dwordx4 v[194:197], v[46:47], off offset:64
	global_load_dwordx4 v[198:201], v[48:49], off offset:64
	s_waitcnt vmcnt(2)
	v_pk_fma_f32 v[52:53], v[30:31], v[58:59], v[52:53]
	v_pk_fma_f32 v[50:51], v[28:29], v[56:57], v[50:51]
	global_store_dwordx4 v[46:47], v[50:53], off
	s_waitcnt vmcnt(1)
	v_pk_fma_f32 v[196:197], v[26:27], v[200:201], v[196:197]
	v_pk_fma_f32 v[194:195], v[24:25], v[198:199], v[194:195]
	global_store_dwordx4 v[46:47], v[194:197], off offset:64

.LBB0_873:
	global_load_dwordx4 v[38:41], v[26:27], off
	global_load_dwordx4 v[46:49], v[28:29], off
	global_load_dwordx4 v[194:197], v[26:27], off offset:64
	global_load_dwordx4 v[198:201], v[28:29], off offset:64
	s_waitcnt vmcnt(2)
	v_pk_fma_f32 v[40:41], v[22:23], v[48:49], v[40:41]
	v_pk_fma_f32 v[38:39], v[20:21], v[46:47], v[38:39]
	global_store_dwordx4 v[24:25], v[38:41], off
	s_waitcnt vmcnt(1)
	v_pk_fma_f32 v[196:197], v[18:19], v[200:201], v[196:197]
	v_pk_fma_f32 v[194:195], v[16:17], v[198:199], v[194:195]
	global_store_dwordx4 v[24:25], v[194:197], off offset:64

.LBB0_915:
	global_load_dwordx4 v[28:31], v[24:25], off
	global_load_dwordx4 v[34:37], v[26:27], off
	global_load_dwordx4 v[194:197], v[24:25], off offset:64
	global_load_dwordx4 v[198:201], v[26:27], off offset:64
	s_waitcnt vmcnt(2)
	v_pk_fma_f32 v[30:31], v[22:23], v[36:37], v[30:31]
	v_pk_fma_f32 v[28:29], v[20:21], v[34:35], v[28:29]
	global_store_dwordx4 v[24:25], v[28:31], off
	s_waitcnt vmcnt(1)
	v_pk_fma_f32 v[196:197], v[18:19], v[200:201], v[196:197]
	v_pk_fma_f32 v[194:195], v[16:17], v[198:199], v[194:195]
	global_store_dwordx4 v[24:25], v[194:197], off offset:64

.LBB0_932:
	global_load_dwordx4 v[32:35], v[20:21], off
	global_load_dwordx4 v[36:39], v[30:31], off
	global_load_dwordx4 v[194:197], v[20:21], off offset:64
	global_load_dwordx4 v[198:201], v[30:31], off offset:64
	s_waitcnt vmcnt(2)
	v_pk_fma_f32 v[34:35], v[14:15], v[38:39], v[34:35]
	v_pk_fma_f32 v[32:33], v[12:13], v[36:37], v[32:33]
	global_store_dwordx4 v[16:17], v[32:35], off
	s_waitcnt vmcnt(1)
	v_pk_fma_f32 v[196:197], v[10:11], v[200:201], v[196:197]
	v_pk_fma_f32 v[194:195], v[8:9], v[198:199], v[194:195]
	global_store_dwordx4 v[16:17], v[194:197], off offset:64

.LBB0_974:
	global_load_dwordx4 v[34:37], v[30:31], off
	global_load_dwordx4 v[40:43], v[32:33], off
	global_load_dwordx4 v[194:197], v[30:31], off offset:64
	global_load_dwordx4 v[198:201], v[32:33], off offset:64
	s_waitcnt vmcnt(2)
	v_pk_fma_f32 v[36:37], v[14:15], v[42:43], v[36:37]
	v_pk_fma_f32 v[34:35], v[12:13], v[40:41], v[34:35]
	global_store_dwordx4 v[30:31], v[34:37], off
	s_waitcnt vmcnt(1)
	v_pk_fma_f32 v[196:197], v[10:11], v[200:201], v[196:197]
	v_pk_fma_f32 v[194:195], v[8:9], v[198:199], v[194:195]
	global_store_dwordx4 v[30:31], v[194:197], off offset:64

.LBB0_991:
	global_load_dwordx4 v[22:25], v[10:11], off
	global_load_dwordx4 v[30:33], v[12:13], off
	global_load_dwordx4 v[194:197], v[10:11], off offset:64
	global_load_dwordx4 v[198:201], v[12:13], off offset:64
	s_waitcnt vmcnt(2)
	v_pk_fma_f32 v[24:25], v[6:7], v[32:33], v[24:25]
	v_pk_fma_f32 v[22:23], v[4:5], v[30:31], v[22:23]
	global_store_dwordx4 v[8:9], v[22:25], off
	s_waitcnt vmcnt(1)
	v_pk_fma_f32 v[196:197], v[2:3], v[200:201], v[196:197]
	v_pk_fma_f32 v[194:195], v[0:1], v[198:199], v[194:195]
	global_store_dwordx4 v[8:9], v[194:197], off offset:64

.LBB0_1061:
	global_load_dwordx4 v[12:15], v[8:9], off
	global_load_dwordx4 v[18:21], v[10:11], off
	global_load_dwordx4 v[194:197], v[8:9], off offset:64
	global_load_dwordx4 v[198:201], v[10:11], off offset:64
	s_waitcnt vmcnt(2)
	v_pk_fma_f32 v[14:15], v[6:7], v[20:21], v[14:15]
	v_pk_fma_f32 v[12:13], v[4:5], v[18:19], v[12:13]
	global_store_dwordx4 v[8:9], v[12:15], off
	s_waitcnt vmcnt(1)
	v_pk_fma_f32 v[196:197], v[2:3], v[200:201], v[196:197]
	v_pk_fma_f32 v[194:195], v[0:1], v[198:199], v[194:195]
	global_store_dwordx4 v[8:9], v[194:197], off offset:64

.LBB0_1219:
	s_andn2_b64 vcc, exec, s[0:1]
	s_cbranch_vccnz .LBB0_1230
	s_add_i32 s0, s91, 0x20068
	v_mov_b32_e32 v0, s0
	ds_read_b32 v0, v0
	s_add_i32 s1, s91, 0x2006c
	s_add_i32 s2, s91, 0x20078
	s_add_i32 s3, s91, 0x2007c
	v_readlane_b32 s4, v254, 20
	s_waitcnt lgkmcnt(0)
	v_readfirstlane_b32 s0, v0
	v_mov_b32_e32 v0, s1
	ds_read_b32 v0, v0
	s_cmpk_gt_i32 s4, 0x41ff
	v_readlane_b32 s5, v254, 21
	s_waitcnt lgkmcnt(0)
	v_readfirstlane_b32 s1, v0
	v_mov_b32_e32 v0, s2
	ds_read_b32 v0, v0
	s_waitcnt lgkmcnt(0)
	v_readfirstlane_b32 s2, v0
	v_mov_b32_e32 v0, s3
	ds_read_b32 v0, v0
	s_waitcnt lgkmcnt(0)
	v_readfirstlane_b32 s3, v0
	s_cbranch_scc1 .LBB0_1230
	v_readlane_b32 s4, v254, 26
	s_lshl_b32 s4, s4, 13
	s_add_u32 s20, s0, s4
	s_addc_u32 s21, s1, 0
	s_add_u32 s22, s2, s4
	s_addc_u32 s23, s3, 0
	v_readlane_b32 s8, v254, 32
	s_mov_b32 s34, s24
	v_readlane_b32 s9, v254, 33
	s_add_u32 s24, s8, 0x15d08000
	s_addc_u32 s25, s9, 0
	s_add_u32 s0, s8, 0x8400000
	s_addc_u32 s1, s9, 0
	s_lshl_b32 s2, s81, 14
	v_readlane_b32 s6, v254, 20
	s_add_i32 s26, s91, s2
	s_ashr_i32 s2, s6, 31
	s_lshr_b32 s2, s2, 26
	s_add_i32 s2, s6, s2
	s_and_b32 s3, s2, 0xffffffc0
	s_sub_i32 s4, s6, s3
	s_lshr_b32 s2, s4, 1
	s_bfe_i32 s5, s2, 0x80000
	s_bfe_u32 s5, s5, 0x4000b
	s_add_i32 s5, s2, s5
	s_and_b32 s5, s5, 0xf0
	s_sub_i32 s2, s2, s5
	s_sext_i32_i8 s2, s2
	v_and_b32_e32 v135, 15, v162
	s_lshl_b32 s2, s2, 6
	v_or_b32_e32 v0, s3, v135
	s_ashr_i32 s3, s2, 31
	s_lshl_b64 s[2:3], s[2:3], 1
	s_add_u32 s2, s0, s2
	v_or_b32_e32 v10, 16, v0
	s_addc_u32 s3, s1, s3
	v_and_b32_e32 v152, 48, v164
	v_ashrrev_i32_e32 v11, 31, v10
	v_lshl_add_u64 v[2:3], s[2:3], 0, v[152:153]
	v_ashrrev_i32_e32 v1, 31, v0
	v_lshlrev_b64 v[10:11], 11, v[10:11]
	v_lshlrev_b64 v[8:9], 11, v[0:1]
	v_lshl_add_u64 v[12:13], v[2:3], 0, v[10:11]
	v_or_b32_e32 v10, 32, v0
	v_or_b32_e32 v0, 48, v0
	v_ashrrev_i32_e32 v1, 31, v0
	v_lshl_or_b32 v4, s4, 6, v135
	v_lshlrev_b64 v[0:1], 11, v[0:1]
	v_lshl_add_u64 v[28:29], v[2:3], 0, v[0:1]
	v_or_b32_e32 v0, 16, v4
	v_lshl_add_u64 v[6:7], s[8:9], 0, v[152:153]
	s_mov_b64 s[2:3], 0x14900000
	v_ashrrev_i32_e32 v1, 31, v0
	v_lshl_add_u64 v[132:133], v[6:7], 0, s[2:3]
	v_lshlrev_b64 v[0:1], 7, v[0:1]
	v_lshl_add_u64 v[44:45], v[132:133], 0, v[0:1]
	v_or_b32_e32 v0, 32, v4
	v_ashrrev_i32_e32 v1, 31, v0
	v_lshlrev_b64 v[0:1], 7, v[0:1]
	v_lshl_add_u64 v[52:53], v[132:133], 0, v[0:1]
	v_or_b32_e32 v0, 48, v4
	v_ashrrev_i32_e32 v5, 31, v4
	v_ashrrev_i32_e32 v11, 31, v10
	v_ashrrev_i32_e32 v1, 31, v0
	v_lshlrev_b64 v[6:7], 7, v[4:5]
	v_lshlrev_b64 v[10:11], 11, v[10:11]
	v_lshlrev_b64 v[0:1], 7, v[0:1]
	v_lshl_add_u64 v[8:9], v[2:3], 0, v[8:9]
	v_lshl_add_u64 v[20:21], v[2:3], 0, v[10:11]
	v_lshl_add_u64 v[36:37], v[132:133], 0, v[6:7]
	v_lshl_add_u64 v[60:61], v[132:133], 0, v[0:1]
	global_load_dwordx4 v[0:3], v[8:9], off
	global_load_dwordx4 v[4:7], v[8:9], off offset:64
	s_nop 0
	global_load_dwordx4 v[8:11], v[12:13], off
	s_nop 0
	global_load_dwordx4 v[12:15], v[12:13], off offset:64
	s_nop 0
	global_load_dwordx4 v[16:19], v[20:21], off
	s_nop 0
	global_load_dwordx4 v[20:23], v[20:21], off offset:64
	s_nop 0
	global_load_dwordx4 v[24:27], v[28:29], off
	s_nop 0
	global_load_dwordx4 v[28:31], v[28:29], off offset:64
	s_nop 0
	global_load_dwordx4 v[32:35], v[36:37], off
	s_nop 0
	global_load_dwordx4 v[36:39], v[36:37], off offset:64
	s_nop 0
	global_load_dwordx4 v[40:43], v[44:45], off
	s_nop 0
	global_load_dwordx4 v[44:47], v[44:45], off offset:64
	s_nop 0
	global_load_dwordx4 v[48:51], v[52:53], off
	s_nop 0
	global_load_dwordx4 v[52:55], v[52:53], off offset:64
	s_nop 0
	global_load_dwordx4 v[56:59], v[60:61], off
	s_nop 0
	global_load_dwordx4 v[60:63], v[60:61], off offset:64
	v_lshrrev_b32_e32 v64, 2, v164
	v_and_b32_e32 v134, 12, v64
	v_bitop3_b32 v157, v64, v135, 12 bitop3:0x6c
	v_bitop3_b32 v159, v134, v135, 1 bitop3:0x36
	v_bitop3_b32 v161, v134, v135, 2 bitop3:0x36
	v_bitop3_b32 v163, v134, v135, 3 bitop3:0x36
	v_bitop3_b32 v182, v134, v135, 16 bitop3:0x36
	v_bitop3_b32 v183, v134, v135, 17 bitop3:0x36
	v_bitop3_b32 v184, v134, v135, 18 bitop3:0x36
	v_bitop3_b32 v185, v134, v135, 19 bitop3:0x36
	v_lshl_add_u32 v64, v135, 8, s26
	v_lshl_add_u64 v[136:137], s[0:1], 0, v[152:153]
	v_lshl_add_u32 v186, v157, 3, v64
	v_lshl_add_u32 v187, v159, 3, v64
	v_lshl_add_u32 v188, v161, 3, v64
	v_lshl_add_u32 v189, v163, 3, v64
	v_lshl_add_u32 v190, v182, 3, v64
	v_lshl_add_u32 v191, v183, 3, v64
	v_lshl_add_u32 v192, v184, 3, v64
	v_lshl_add_u32 v193, v185, 3, v64
	v_cmp_gt_u32_e64 s[4:5], 32, v164
	v_lshlrev_b32_e32 v152, 1, v134
	v_lshlrev_b32_e32 v194, 3, v164
	s_mov_b32 s27, s6
	v_readlane_b32 s7, v254, 21
	s_waitcnt vmcnt(0)
	s_branch .LBB0_1223

.LBB0_1223:
	s_ashr_i32 s2, s27, 31
	s_waitcnt vmcnt(16)
	v_mfma_f32_16x16x32_bf16 v[64:67], v[32:35], v[0:3], 0
	s_lshr_b32 s2, s2, 26
	s_add_i32 s31, s27, s2
	s_and_b32 s2, s31, 0xffffffc0
	s_sub_i32 s30, s27, s2
	v_mfma_f32_16x16x32_bf16 v[124:127], v[36:39], v[4:7], v[64:67]
	s_nop 2
	v_or_b32_e32 v64, s2, v135
	s_lshl_b32 s2, s30, 5
	s_and_b32 s29, s2, 0x3c0
	v_mfma_f32_16x16x32_bf16 v[80:83], v[32:35], v[8:11], 0
	s_and_b32 s28, s2, 32
	s_lshl_b32 s3, s29, 1
	s_add_u32 s3, s0, s3
	v_mfma_f32_16x16x32_bf16 v[142:145], v[40:43], v[16:19], 0
	s_addc_u32 s7, s1, 0
	s_lshl_b32 s6, s28, 1
	s_add_u32 s6, s3, s6
	v_mfma_f32_16x16x32_bf16 v[88:91], v[48:51], v[8:11], 0
	v_ashrrev_i32_e32 v65, 31, v64
	v_or_b32_e32 v150, 16, v64
	s_addc_u32 s7, s7, 0
	v_mfma_f32_16x16x32_bf16 v[138:141], v[32:35], v[16:19], 0
	v_lshlrev_b64 v[130:131], 11, v[64:65]
	v_ashrrev_i32_e32 v151, 31, v150
	v_lshl_add_u64 v[66:67], s[6:7], 0, v[130:131]
	v_mfma_f32_16x16x32_bf16 v[68:71], v[40:43], v[0:3], 0
	v_lshlrev_b64 v[172:173], 11, v[150:151]
	v_lshl_add_u64 v[66:67], v[66:67], 0, v[152:153]
	v_mfma_f32_16x16x32_bf16 v[104:107], v[36:39], v[12:15], v[80:83]
	v_mfma_f32_16x16x32_bf16 v[80:83], v[44:47], v[20:23], v[142:145]
	s_nop 2
	v_or_b32_e32 v142, 32, v64
	v_mfma_f32_16x16x32_bf16 v[92:95], v[56:59], v[8:11], 0
	v_ashrrev_i32_e32 v143, 31, v142
	v_lshlrev_b64 v[166:167], 11, v[142:143]
	v_mfma_f32_16x16x32_bf16 v[146:149], v[48:51], v[16:19], 0
	v_mfma_f32_16x16x32_bf16 v[108:111], v[52:55], v[12:15], v[88:91]
	v_mfma_f32_16x16x32_bf16 v[88:91], v[36:39], v[20:23], v[138:141]
	s_nop 2
	v_or_b32_e32 v140, 48, v64
	v_mfma_f32_16x16x32_bf16 v[112:115], v[44:47], v[4:7], v[68:71]
	v_ashrrev_i32_e32 v141, 31, v140
	v_lshlrev_b64 v[144:145], 11, v[140:141]
	v_lshl_add_u64 v[64:65], s[6:7], 0, v[144:145]
	v_lshl_add_u64 v[68:69], s[6:7], 0, v[172:173]
	v_lshl_add_u64 v[68:69], v[68:69], 0, v[152:153]
	global_load_dwordx2 v[128:129], v[66:67], off
	global_load_dwordx2 v[176:177], v[66:67], off offset:32
	global_load_dwordx2 v[174:175], v[68:69], off
	global_load_dwordx2 v[170:171], v[68:69], off offset:32
	v_lshl_add_u64 v[66:67], s[6:7], 0, v[166:167]
	v_lshl_add_u64 v[66:67], v[66:67], 0, v[152:153]
	v_mfma_f32_16x16x32_bf16 v[100:103], v[60:63], v[12:15], v[92:95]
	v_lshl_add_u64 v[64:65], v[64:65], 0, v[152:153]
	v_readlane_b32 s6, v254, 22
	s_add_i32 s27, s27, s6
	v_mfma_f32_16x16x32_bf16 v[92:95], v[52:55], v[20:23], v[146:149]
	global_load_dwordx2 v[168:169], v[66:67], off
	s_nop 1
	global_load_dwordx2 v[148:149], v[66:67], off offset:32
	global_load_dwordx2 v[146:147], v[64:65], off
	global_load_dwordx2 v[138:139], v[64:65], off offset:32
	s_and_b32 s12, s2, 0x3e0
	s_and_b32 s14, s2, 0xfffffc00
	s_ashr_i32 s15, s14, 31
	s_lshl_b64 s[14:15], s[14:15], 2
	v_or_b32_e32 v224, s12, v134
	v_lshlrev_b32_e32 v224, 2, v224
	s_add_u32 s16, s20, s14
	s_addc_u32 s17, s21, s15
	global_load_dwordx4 v[212:215], v224, s[16:17]
	global_load_dwordx4 v[230:233], v224, s[16:17] offset:64
	s_add_u32 s16, s22, s14
	s_addc_u32 s17, s23, s15
	global_load_dwordx4 v[216:219], v224, s[16:17]
	global_load_dwordx4 v[234:237], v224, s[16:17] offset:64
	s_add_u32 s16, s24, s14
	s_addc_u32 s17, s25, s15
	global_load_dwordx4 v[220:223], v224, s[16:17]
	global_load_dwordx4 v[244:247], v224, s[16:17] offset:64
	v_readlane_b32 s7, v254, 23
	s_cmpk_gt_i32 s27, 0x41ff
	v_mfma_f32_16x16x32_bf16 v[72:75], v[48:51], v[0:3], 0
	s_cselect_b64 s[6:7], -1, 0
	s_and_b64 vcc, exec, s[6:7]
	v_mfma_f32_16x16x32_bf16 v[76:79], v[56:59], v[0:3], 0
	v_mfma_f32_16x16x32_bf16 v[84:87], v[40:43], v[8:11], 0
	v_mfma_f32_16x16x32_bf16 v[178:181], v[56:59], v[16:19], 0
	v_mfma_f32_16x16x32_bf16 v[196:199], v[32:35], v[24:27], 0
	v_mfma_f32_16x16x32_bf16 v[200:203], v[40:43], v[24:27], 0
	v_mfma_f32_16x16x32_bf16 v[204:207], v[48:51], v[24:27], 0
	v_mfma_f32_16x16x32_bf16 v[208:211], v[56:59], v[24:27], 0
	v_mfma_f32_16x16x32_bf16 v[120:123], v[52:55], v[4:7], v[72:75]
	v_mfma_f32_16x16x32_bf16 v[116:119], v[60:63], v[4:7], v[76:79]
	v_mfma_f32_16x16x32_bf16 v[96:99], v[44:47], v[12:15], v[84:87]
	v_mfma_f32_16x16x32_bf16 v[84:87], v[60:63], v[20:23], v[178:181]
	v_mfma_f32_16x16x32_bf16 v[72:75], v[36:39], v[28:31], v[196:199]
	v_mfma_f32_16x16x32_bf16 v[68:71], v[44:47], v[28:31], v[200:203]
	v_mfma_f32_16x16x32_bf16 v[76:79], v[52:55], v[28:31], v[204:207]
	v_mfma_f32_16x16x32_bf16 v[64:67], v[60:63], v[28:31], v[208:211]
	s_cbranch_vccnz .Lrg_nopf
	s_ashr_i32 s3, s27, 31
	s_lshr_b32 s3, s3, 26
	s_add_i32 s3, s27, s3
	s_andn2_b32 s3, s3, 63
	s_sub_i32 s10, s27, s3
	s_lshr_b32 s8, s10, 1
	s_bfe_i32 s9, s8, 0x80000
	s_bfe_u32 s9, s9, 0x4000b
	s_add_i32 s9, s8, s9
	s_and_b32 s9, s9, 0xf0
	s_sub_i32 s8, s8, s9
	s_sext_i32_i8 s8, s8
	v_or_b32_e32 v0, s3, v135
	s_lshl_b32 s8, s8, 6
	v_or_b32_e32 v10, 16, v0
	s_ashr_i32 s9, s8, 31
	v_ashrrev_i32_e32 v11, 31, v10
	v_lshl_add_u64 v[2:3], s[8:9], 1, v[136:137]
	v_ashrrev_i32_e32 v1, 31, v0
	v_lshlrev_b64 v[10:11], 11, v[10:11]
	v_lshlrev_b64 v[8:9], 11, v[0:1]
	v_lshl_add_u64 v[12:13], v[2:3], 0, v[10:11]
	v_or_b32_e32 v10, 32, v0
	v_or_b32_e32 v0, 48, v0
	v_ashrrev_i32_e32 v1, 31, v0
	v_lshl_or_b32 v4, s10, 6, v135
	v_lshlrev_b64 v[0:1], 11, v[0:1]
	v_lshl_add_u64 v[28:29], v[2:3], 0, v[0:1]
	v_or_b32_e32 v0, 16, v4
	v_ashrrev_i32_e32 v1, 31, v0
	v_lshlrev_b64 v[0:1], 7, v[0:1]
	v_lshl_add_u64 v[44:45], v[132:133], 0, v[0:1]
	v_or_b32_e32 v0, 32, v4
	v_ashrrev_i32_e32 v1, 31, v0
	v_lshlrev_b64 v[0:1], 7, v[0:1]
	v_lshl_add_u64 v[52:53], v[132:133], 0, v[0:1]
	v_or_b32_e32 v0, 48, v4
	v_ashrrev_i32_e32 v5, 31, v4
	v_ashrrev_i32_e32 v11, 31, v10
	v_ashrrev_i32_e32 v1, 31, v0
	v_lshlrev_b64 v[6:7], 7, v[4:5]
	v_lshlrev_b64 v[10:11], 11, v[10:11]
	v_lshlrev_b64 v[0:1], 7, v[0:1]
	v_lshl_add_u64 v[8:9], v[2:3], 0, v[8:9]
	v_lshl_add_u64 v[20:21], v[2:3], 0, v[10:11]
	v_lshl_add_u64 v[36:37], v[132:133], 0, v[6:7]
	v_lshl_add_u64 v[60:61], v[132:133], 0, v[0:1]
	global_load_dwordx4 v[0:3], v[8:9], off
	global_load_dwordx4 v[4:7], v[8:9], off offset:64
	s_nop 0
	global_load_dwordx4 v[8:11], v[12:13], off
	s_nop 0
	global_load_dwordx4 v[12:15], v[12:13], off offset:64
	s_nop 0
	global_load_dwordx4 v[16:19], v[20:21], off
	s_nop 0
	global_load_dwordx4 v[20:23], v[20:21], off offset:64
	s_nop 0
	global_load_dwordx4 v[24:27], v[28:29], off
	s_nop 0
	global_load_dwordx4 v[28:31], v[28:29], off offset:64
	s_nop 0
	global_load_dwordx4 v[32:35], v[36:37], off
	s_nop 0
	global_load_dwordx4 v[36:39], v[36:37], off offset:64
	s_nop 0
	global_load_dwordx4 v[40:43], v[44:45], off
	s_nop 0
	global_load_dwordx4 v[44:47], v[44:45], off offset:64
	s_nop 0
	global_load_dwordx4 v[48:51], v[52:53], off
	s_nop 0
	global_load_dwordx4 v[52:55], v[52:53], off offset:64
	s_nop 0
	global_load_dwordx4 v[56:59], v[60:61], off
	s_nop 0
	global_load_dwordx4 v[60:63], v[60:61], off offset:64
	s_waitcnt vmcnt(16)
	s_branch .LBB0_1225

.LBB0_1225:
	s_and_b32 s12, s2, 0x3e0
	s_and_b32 s2, s2, 0xfffffc00
	s_ashr_i32 s3, s2, 31
	s_cmp_lt_u32 s30, 32
	s_cselect_b64 s[8:9], -1, 0
	s_and_b64 s[10:11], s[8:9], exec
	s_mov_b32 s10, 0x4200000
	v_readlane_b32 s11, v254, 26
	s_cselect_b32 s10, 0xc600000, s10
	v_or_b32_e32 v143, s12, v134
	s_mul_i32 s11, s11, 0x10800000
	v_readlane_b32 s12, v254, 32
	s_cselect_b32 s11, 0xe700000, s11
	v_readlane_b32 s13, v254, 33
	s_add_u32 s18, s12, s10
	s_addc_u32 s19, s13, 0
	s_add_u32 s16, s12, s11
	s_addc_u32 s17, s13, 0
	s_lshl_b64 s[2:3], s[2:3], 2
	s_add_u32 s14, s20, s2
	s_addc_u32 s15, s21, s3
	v_lshlrev_b32_e32 v141, 2, v143
	s_add_u32 s12, s22, s2
	s_addc_u32 s13, s23, s3
	s_add_u32 s10, s24, s2
	s_addc_u32 s11, s25, s3
	v_lshlrev_b32_e32 v151, 16, v128
	v_and_b32_e32 v178, 0xffff0000, v129
	v_lshlrev_b32_e32 v143, 1, v143
	v_or_b32_e32 v130, v130, v143
	v_lshl_add_u64 v[180:181], s[18:19], 0, v[130:131]
	v_or_b32_e32 v172, v172, v143
	v_or_b32_e32 v166, v166, v143
	v_or_b32_e32 v144, v144, v143
	v_add_f32_e32 v124, v124, v212
	v_add_f32_e32 v125, v125, v213
	v_add_f32_e32 v126, v126, v214
	v_add_f32_e32 v127, v127, v215
	v_mul_f32_e32 v124, 0xbfb8aa3b, v124
	v_mul_f32_e32 v125, 0xbfb8aa3b, v125
	v_mul_f32_e32 v126, 0xbfb8aa3b, v126
	v_mul_f32_e32 v127, 0xbfb8aa3b, v127
	v_exp_f32_e32 v124, v124
	v_exp_f32_e32 v125, v125
	v_exp_f32_e32 v126, v126
	v_add_f32_e32 v120, v120, v216
	v_add_f32_e32 v121, v121, v217
	v_add_f32_e32 v122, v122, v218
	v_exp_f32_e32 v127, v127
	v_add_f32_e32 v123, v123, v219
	v_mul_f32_e32 v120, 0xbfb8aa3b, v120
	v_mul_f32_e32 v121, 0xbfb8aa3b, v121
	v_mul_f32_e32 v122, 0xbfb8aa3b, v122
	v_mul_f32_e32 v123, 0xbfb8aa3b, v123
	v_exp_f32_e32 v120, v120
	v_exp_f32_e32 v121, v121
	v_exp_f32_e32 v122, v122
	v_exp_f32_e32 v123, v123
	v_add_f32_e32 v124, 1.0, v124
	v_add_f32_e32 v125, 1.0, v125
	v_add_f32_e32 v126, 1.0, v126
	v_add_f32_e32 v127, 1.0, v127
	v_rcp_f32_e32 v124, v124
	v_rcp_f32_e32 v125, v125
	v_rcp_f32_e32 v126, v126
	v_rcp_f32_e32 v127, v127
	v_add_f32_e32 v120, 1.0, v120
	v_add_f32_e32 v121, 1.0, v121
	v_add_f32_e32 v122, 1.0, v122
	v_add_f32_e32 v123, 1.0, v123
	v_rcp_f32_e32 v179, v120
	v_rcp_f32_e32 v120, v121
	v_rcp_f32_e32 v121, v122
	v_rcp_f32_e32 v122, v123
	v_mul_f32_e64 v123, v124, -v220
	v_mul_f32_e64 v124, v125, -v221
	v_mul_f32_e64 v125, v126, -v222
	v_mul_f32_e64 v126, v127, -v223
	v_mul_f32_e32 v127, 0x3fb8aa3b, v123
	v_add_f32_e32 v123, v123, v123
	v_mul_f32_e32 v195, 0x3fb8aa3b, v124
	v_add_f32_e32 v124, v124, v124
	v_mul_f32_e32 v196, 0x3fb8aa3b, v125
	v_add_f32_e32 v125, v125, v125
	v_mul_f32_e32 v197, 0x3fb8aa3b, v126
	v_add_f32_e32 v126, v126, v126
	v_mul_f32_e32 v123, 0x3fb8aa3b, v123
	v_mul_f32_e32 v124, 0x3fb8aa3b, v124
	v_mul_f32_e32 v125, 0x3fb8aa3b, v125
	v_mul_f32_e32 v199, v179, v151
	v_exp_f32_e32 v179, v196
	v_mul_f32_e32 v196, 0x3fb8aa3b, v126
	v_mul_f32_e32 v126, v122, v178
	v_exp_f32_e32 v122, v123
	v_exp_f32_e32 v123, v124
	v_exp_f32_e32 v124, v125
	v_exp_f32_e32 v125, v196
	v_exp_f32_e32 v127, v127
	v_exp_f32_e32 v151, v195
	v_exp_f32_e32 v195, v197
	v_sub_f32_e32 v122, 1.0, v122
	v_sub_f32_e32 v123, 1.0, v123
	v_sub_f32_e32 v124, 1.0, v124
	v_sub_f32_e32 v125, 1.0, v125
	v_max_f32_e32 v122, 0, v122
	v_max_f32_e32 v123, 0, v123
	v_max_f32_e32 v124, 0, v124
	v_sub_f32_e32 v196, 1.0, v127
	v_sub_f32_e32 v197, 1.0, v151
	v_sub_f32_e32 v198, 1.0, v179
	v_sub_f32_e32 v151, 1.0, v195
	v_max_f32_e32 v125, 0, v125
	v_sqrt_f32_e32 v195, v122
	v_sqrt_f32_e32 v122, v123
	v_sqrt_f32_e32 v123, v124
	v_sqrt_f32_e32 v127, v125
	v_cvt_pk_f16_f32 v125, v198, v151
	v_cvt_pk_f16_f32 v124, v196, v197
	global_store_dwordx2 v[180:181], v[124:125], off
	v_and_b32_e32 v124, 0xffff0000, v128
	v_lshlrev_b32_e32 v125, 16, v129
	v_pk_mul_f32 v[120:121], v[120:121], v[124:125]
	v_fma_mixlo_f16 v195, v199, v195, 0
	v_pk_mul_f32 v[120:121], v[120:121], v[122:123]
	v_fma_mixlo_f16 v200, v126, v127, 0
	v_cvt_pk_f16_f32 v199, v120, v121
	v_lshl_add_u64 v[178:179], s[16:17], 0, v[130:131]
	v_pack_b32_f16 v120, v195, v199
	v_alignbit_b32 v121, v200, v199, 16
	global_store_dwordx2 v[178:179], v[120:121], off
	s_nop 0
	v_lshlrev_b32_e32 v201, 16, v176
	v_and_b32_e32 v202, 0xffff0000, v177
	v_and_b32_e32 v176, 0xffff0000, v176
	v_lshlrev_b32_e32 v177, 16, v177
	v_cvt_f16_f32_e32 v196, v196
	v_cvt_f16_f32_e32 v197, v197
	v_cvt_f16_f32_e32 v198, v198
	v_add_f32_e32 v112, v112, v230
	v_add_f32_e32 v116, v116, v234
	v_add_f32_e32 v113, v113, v231
	v_add_f32_e32 v114, v114, v232
	v_add_f32_e32 v117, v117, v235
	v_add_f32_e32 v115, v115, v233
	v_add_f32_e32 v119, v119, v237
	v_mul_f32_e32 v112, 0xbfb8aa3b, v112
	v_mul_f32_e32 v116, 0xbfb8aa3b, v116
	v_mul_f32_e32 v113, 0xbfb8aa3b, v113
	v_mul_f32_e32 v114, 0xbfb8aa3b, v114
	v_mul_f32_e32 v117, 0xbfb8aa3b, v117
	v_mul_f32_e32 v115, 0xbfb8aa3b, v115
	v_mul_f32_e32 v119, 0xbfb8aa3b, v119
	v_exp_f32_e32 v112, v112
	v_exp_f32_e32 v116, v116
	v_exp_f32_e32 v113, v113
	v_exp_f32_e32 v114, v114
	v_exp_f32_e32 v117, v117
	v_exp_f32_e32 v115, v115
	v_exp_f32_e32 v119, v119
	v_add_f32_e32 v118, v118, v236
	v_mul_f32_e32 v118, 0xbfb8aa3b, v118
	v_exp_f32_e32 v118, v118
	v_add_f32_e32 v112, 1.0, v112
	v_add_f32_e32 v116, 1.0, v116
	v_add_f32_e32 v113, 1.0, v113
	v_add_f32_e32 v114, 1.0, v114
	v_add_f32_e32 v117, 1.0, v117
	v_add_f32_e32 v115, 1.0, v115
	v_add_f32_e32 v119, 1.0, v119
	v_rcp_f32_e32 v124, v112
	v_rcp_f32_e32 v116, v116
	v_rcp_f32_e32 v125, v113
	v_rcp_f32_e32 v114, v114
	v_rcp_f32_e32 v112, v117
	v_rcp_f32_e32 v115, v115
	v_rcp_f32_e32 v117, v119
	v_add_f32_e32 v118, 1.0, v118
	v_rcp_f32_e32 v113, v118
	v_mul_f32_e64 v118, v124, -v244
	v_mul_f32_e32 v119, v116, v201
	v_mul_f32_e64 v116, v125, -v245
	v_mul_f32_e64 v114, v114, -v246
	v_mul_f32_e64 v115, v115, -v247
	v_mul_f32_e32 v120, v117, v202
	v_mul_f32_e32 v117, 0x3fb8aa3b, v118
	v_add_f32_e32 v118, v118, v118
	v_mul_f32_e32 v121, 0x3fb8aa3b, v116
	v_add_f32_e32 v116, v116, v116
	v_mul_f32_e32 v122, 0x3fb8aa3b, v114
	v_add_f32_e32 v114, v114, v114
	v_mul_f32_e32 v123, 0x3fb8aa3b, v115
	v_add_f32_e32 v115, v115, v115
	v_mul_f32_e32 v118, 0x3fb8aa3b, v118
	v_mul_f32_e32 v116, 0x3fb8aa3b, v116
	v_mul_f32_e32 v114, 0x3fb8aa3b, v114
	v_exp_f32_e32 v117, v117
	v_mul_f32_e32 v115, 0x3fb8aa3b, v115
	v_exp_f32_e32 v118, v118
	v_exp_f32_e32 v116, v116
	v_exp_f32_e32 v114, v114
	v_exp_f32_e32 v121, v121
	v_exp_f32_e32 v115, v115
	v_exp_f32_e32 v122, v122
	v_sub_f32_e32 v128, 1.0, v117
	v_sub_f32_e32 v117, 1.0, v118
	v_sub_f32_e32 v116, 1.0, v116
	v_sub_f32_e32 v118, 1.0, v114
	v_exp_f32_e32 v123, v123
	v_sub_f32_e32 v129, 1.0, v121
	v_sub_f32_e32 v121, 1.0, v115
	v_max_f32_e32 v117, 0, v117
	v_max_f32_e32 v116, 0, v116
	v_max_f32_e32 v118, 0, v118
	v_sub_f32_e32 v130, 1.0, v122
	v_max_f32_e32 v121, 0, v121
	v_sqrt_f32_e32 v122, v117
	v_sqrt_f32_e32 v116, v116
	v_sqrt_f32_e32 v117, v118
	v_sqrt_f32_e32 v118, v121
	v_pk_mul_f32 v[112:113], v[112:113], v[176:177]
	v_sub_f32_e32 v131, 1.0, v123
	v_cvt_pk_f16_f32 v115, v130, v131
	v_cvt_pk_f16_f32 v114, v128, v129
	v_pk_mul_f32 v[112:113], v[112:113], v[116:117]
	global_store_dwordx2 v[180:181], v[114:115], off offset:32
	v_fma_mixlo_f16 v176, v119, v122, 0
	v_fma_mixlo_f16 v180, v120, v118, 0
	v_cvt_pk_f16_f32 v177, v112, v113
	v_pack_b32_f16 v112, v176, v177
	v_alignbit_b32 v113, v180, v177, 16
	global_store_dwordx2 v[178:179], v[112:113], off offset:32
	s_nop 0
	v_lshlrev_b32_e32 v178, 16, v174
	v_and_b32_e32 v179, 0xffff0000, v175
	v_and_b32_e32 v174, 0xffff0000, v174
	v_lshlrev_b32_e32 v175, 16, v175
	v_lshl_add_u64 v[126:127], s[18:19], 0, v[172:173]
	v_lshl_add_u64 v[124:125], s[16:17], 0, v[172:173]
	v_and_b32_e32 v172, 0xffff0000, v171
	v_lshlrev_b32_e32 v171, 16, v171
	v_add_f32_e32 v104, v104, v212
	v_add_f32_e32 v108, v108, v216
	v_add_f32_e32 v105, v105, v213
	v_add_f32_e32 v106, v106, v214
	v_add_f32_e32 v109, v109, v217
	v_add_f32_e32 v107, v107, v215
	v_add_f32_e32 v111, v111, v219
	v_mul_f32_e32 v104, 0xbfb8aa3b, v104
	v_mul_f32_e32 v108, 0xbfb8aa3b, v108
	v_mul_f32_e32 v105, 0xbfb8aa3b, v105
	v_mul_f32_e32 v106, 0xbfb8aa3b, v106
	v_mul_f32_e32 v109, 0xbfb8aa3b, v109
	v_mul_f32_e32 v107, 0xbfb8aa3b, v107
	v_mul_f32_e32 v111, 0xbfb8aa3b, v111
	v_exp_f32_e32 v104, v104
	v_exp_f32_e32 v108, v108
	v_exp_f32_e32 v105, v105
	v_exp_f32_e32 v106, v106
	v_exp_f32_e32 v109, v109
	v_exp_f32_e32 v107, v107
	v_exp_f32_e32 v111, v111
	v_add_f32_e32 v110, v110, v218
	v_mul_f32_e32 v110, 0xbfb8aa3b, v110
	v_exp_f32_e32 v110, v110
	v_add_f32_e32 v104, 1.0, v104
	v_add_f32_e32 v108, 1.0, v108
	v_add_f32_e32 v105, 1.0, v105
	v_add_f32_e32 v106, 1.0, v106
	v_add_f32_e32 v109, 1.0, v109
	v_add_f32_e32 v107, 1.0, v107
	v_add_f32_e32 v111, 1.0, v111
	v_rcp_f32_e32 v116, v104
	v_rcp_f32_e32 v108, v108
	v_rcp_f32_e32 v117, v105
	v_rcp_f32_e32 v106, v106
	v_rcp_f32_e32 v104, v109
	v_rcp_f32_e32 v107, v107
	v_rcp_f32_e32 v109, v111
	v_add_f32_e32 v110, 1.0, v110
	v_rcp_f32_e32 v105, v110
	v_mul_f32_e64 v110, v116, -v220
	v_mul_f32_e32 v111, v108, v178
	v_mul_f32_e64 v108, v117, -v221
	v_mul_f32_e64 v106, v106, -v222
	v_mul_f32_e64 v107, v107, -v223
	v_mul_f32_e32 v112, v109, v179
	v_mul_f32_e32 v109, 0x3fb8aa3b, v110
	v_add_f32_e32 v110, v110, v110
	v_mul_f32_e32 v113, 0x3fb8aa3b, v108
	v_add_f32_e32 v108, v108, v108
	v_mul_f32_e32 v114, 0x3fb8aa3b, v106
	v_add_f32_e32 v106, v106, v106
	v_mul_f32_e32 v115, 0x3fb8aa3b, v107
	v_add_f32_e32 v107, v107, v107
	v_mul_f32_e32 v110, 0x3fb8aa3b, v110
	v_mul_f32_e32 v108, 0x3fb8aa3b, v108
	v_mul_f32_e32 v106, 0x3fb8aa3b, v106
	v_exp_f32_e32 v109, v109
	v_mul_f32_e32 v107, 0x3fb8aa3b, v107
	v_exp_f32_e32 v110, v110
	v_exp_f32_e32 v108, v108
	v_exp_f32_e32 v106, v106
	v_exp_f32_e32 v113, v113
	v_exp_f32_e32 v107, v107
	v_exp_f32_e32 v114, v114
	v_sub_f32_e32 v116, 1.0, v109
	v_sub_f32_e32 v109, 1.0, v110
	v_sub_f32_e32 v108, 1.0, v108
	v_sub_f32_e32 v110, 1.0, v106
	v_sub_f32_e32 v117, 1.0, v113
	v_sub_f32_e32 v113, 1.0, v107
	v_max_f32_e32 v109, 0, v109
	v_max_f32_e32 v108, 0, v108
	v_max_f32_e32 v110, 0, v110
	v_sub_f32_e32 v118, 1.0, v114
	v_max_f32_e32 v113, 0, v113
	v_sqrt_f32_e32 v114, v109
	v_sqrt_f32_e32 v108, v108
	v_sqrt_f32_e32 v109, v110
	v_exp_f32_e32 v115, v115
	v_sqrt_f32_e32 v110, v113
	v_pk_mul_f32 v[104:105], v[104:105], v[174:175]
	v_fma_mixlo_f16 v120, v111, v114, 0
	v_pk_mul_f32 v[104:105], v[104:105], v[108:109]
	v_sub_f32_e32 v119, 1.0, v115
	v_fma_mixlo_f16 v122, v112, v110, 0
	v_cvt_pk_f16_f32 v121, v104, v105
	v_cvt_pk_f16_f32 v107, v118, v119
	v_cvt_pk_f16_f32 v106, v116, v117
	v_pack_b32_f16 v104, v120, v121
	v_alignbit_b32 v105, v122, v121, 16
	global_store_dwordx2 v[126:127], v[106:107], off
	global_store_dwordx2 v[124:125], v[104:105], off
	s_nop 0
	v_lshlrev_b32_e32 v123, 16, v170
	v_and_b32_e32 v170, 0xffff0000, v170
	v_add_f32_e32 v96, v96, v230
	v_add_f32_e32 v100, v100, v234
	v_add_f32_e32 v97, v97, v231
	v_add_f32_e32 v98, v98, v232
	v_add_f32_e32 v101, v101, v235
	v_add_f32_e32 v99, v99, v233
	v_add_f32_e32 v103, v103, v237
	v_mul_f32_e32 v96, 0xbfb8aa3b, v96
	v_mul_f32_e32 v100, 0xbfb8aa3b, v100
	v_mul_f32_e32 v97, 0xbfb8aa3b, v97
	v_mul_f32_e32 v98, 0xbfb8aa3b, v98
	v_mul_f32_e32 v101, 0xbfb8aa3b, v101
	v_mul_f32_e32 v99, 0xbfb8aa3b, v99
	v_mul_f32_e32 v103, 0xbfb8aa3b, v103
	v_exp_f32_e32 v96, v96
	v_exp_f32_e32 v100, v100
	v_exp_f32_e32 v97, v97
	v_exp_f32_e32 v98, v98
	v_exp_f32_e32 v101, v101
	v_exp_f32_e32 v99, v99
	v_exp_f32_e32 v103, v103
	v_add_f32_e32 v102, v102, v236
	v_mul_f32_e32 v102, 0xbfb8aa3b, v102
	v_exp_f32_e32 v102, v102
	v_add_f32_e32 v96, 1.0, v96
	v_add_f32_e32 v100, 1.0, v100
	v_add_f32_e32 v97, 1.0, v97
	v_add_f32_e32 v98, 1.0, v98
	v_add_f32_e32 v101, 1.0, v101
	v_add_f32_e32 v99, 1.0, v99
	v_add_f32_e32 v103, 1.0, v103
	v_rcp_f32_e32 v108, v96
	v_rcp_f32_e32 v100, v100
	v_rcp_f32_e32 v109, v97
	v_rcp_f32_e32 v98, v98
	v_rcp_f32_e32 v96, v101
	v_rcp_f32_e32 v99, v99
	v_rcp_f32_e32 v101, v103
	v_add_f32_e32 v102, 1.0, v102
	v_rcp_f32_e32 v97, v102
	v_mul_f32_e64 v102, v108, -v244
	v_mul_f32_e32 v103, v100, v123
	v_mul_f32_e64 v100, v109, -v245
	v_mul_f32_e64 v98, v98, -v246
	v_mul_f32_e64 v99, v99, -v247
	v_mul_f32_e32 v104, v101, v172
	v_mul_f32_e32 v101, 0x3fb8aa3b, v102
	v_add_f32_e32 v102, v102, v102
	v_mul_f32_e32 v105, 0x3fb8aa3b, v100
	v_add_f32_e32 v100, v100, v100
	v_mul_f32_e32 v106, 0x3fb8aa3b, v98
	v_add_f32_e32 v98, v98, v98
	v_mul_f32_e32 v107, 0x3fb8aa3b, v99
	v_add_f32_e32 v99, v99, v99
	v_mul_f32_e32 v102, 0x3fb8aa3b, v102
	v_mul_f32_e32 v100, 0x3fb8aa3b, v100
	v_mul_f32_e32 v98, 0x3fb8aa3b, v98
	v_exp_f32_e32 v101, v101
	v_mul_f32_e32 v99, 0x3fb8aa3b, v99
	v_exp_f32_e32 v102, v102
	v_exp_f32_e32 v100, v100
	v_exp_f32_e32 v98, v98
	v_exp_f32_e32 v105, v105
	v_exp_f32_e32 v99, v99
	v_exp_f32_e32 v106, v106
	v_pk_mul_f32 v[96:97], v[96:97], v[170:171]
	v_sub_f32_e32 v170, 1.0, v101
	v_sub_f32_e32 v101, 1.0, v102
	v_sub_f32_e32 v100, 1.0, v100
	v_sub_f32_e32 v102, 1.0, v98
	v_exp_f32_e32 v107, v107
	v_sub_f32_e32 v171, 1.0, v105
	v_sub_f32_e32 v105, 1.0, v99
	v_max_f32_e32 v101, 0, v101
	v_max_f32_e32 v100, 0, v100
	v_max_f32_e32 v102, 0, v102
	v_sub_f32_e32 v172, 1.0, v106
	v_max_f32_e32 v105, 0, v105
	v_sqrt_f32_e32 v106, v101
	v_sqrt_f32_e32 v100, v100
	v_sqrt_f32_e32 v101, v102
	v_sqrt_f32_e32 v102, v105
	v_sub_f32_e32 v173, 1.0, v107
	v_cvt_pk_f16_f32 v99, v172, v173
	v_cvt_pk_f16_f32 v98, v170, v171
	v_pk_mul_f32 v[96:97], v[96:97], v[100:101]
	global_store_dwordx2 v[126:127], v[98:99], off offset:32
	v_fma_mixlo_f16 v126, v103, v106, 0
	v_fma_mixlo_f16 v174, v104, v102, 0
	v_cvt_pk_f16_f32 v127, v96, v97
	v_pack_b32_f16 v96, v126, v127
	v_alignbit_b32 v97, v174, v127, 16
	global_store_dwordx2 v[124:125], v[96:97], off offset:32
	s_nop 0
	v_lshlrev_b32_e32 v114, 16, v168
	v_and_b32_e32 v115, 0xffff0000, v169
	v_lshl_add_u64 v[110:111], s[18:19], 0, v[166:167]
	v_lshl_add_u64 v[108:109], s[16:17], 0, v[166:167]
	v_and_b32_e32 v112, 0xffff0000, v168
	v_lshlrev_b32_e32 v113, 16, v169
	v_lshlrev_b32_e32 v167, 16, v148
	v_lshlrev_b32_e32 v125, 8, v150
	v_and_b32_e32 v150, 0xffff0000, v149
	v_and_b32_e32 v168, 0xffff0000, v148
	v_lshlrev_b32_e32 v169, 16, v149
	v_and_b32_e32 v125, 0x1f00, v125
	v_lshlrev_b32_e32 v124, 3, v157
	v_add_u32_e32 v125, s26, v125
	v_lshlrev_b32_e32 v123, 3, v159
	v_lshlrev_b32_e32 v149, 16, v146
	v_add_u32_e32 v175, v125, v124
	v_add_u32_e32 v178, v125, v123
	v_and_b32_e32 v148, 0xffff0000, v147
	v_add_f32_e32 v88, v88, v212
	v_add_f32_e32 v92, v92, v216
	v_add_f32_e32 v89, v89, v213
	v_add_f32_e32 v90, v90, v214
	v_add_f32_e32 v93, v93, v217
	v_add_f32_e32 v91, v91, v215
	v_add_f32_e32 v95, v95, v219
	v_mul_f32_e32 v88, 0xbfb8aa3b, v88
	v_mul_f32_e32 v92, 0xbfb8aa3b, v92
	v_mul_f32_e32 v89, 0xbfb8aa3b, v89
	v_mul_f32_e32 v90, 0xbfb8aa3b, v90
	v_mul_f32_e32 v93, 0xbfb8aa3b, v93
	v_mul_f32_e32 v91, 0xbfb8aa3b, v91
	v_mul_f32_e32 v95, 0xbfb8aa3b, v95
	v_exp_f32_e32 v88, v88
	v_exp_f32_e32 v92, v92
	v_exp_f32_e32 v89, v89
	v_exp_f32_e32 v90, v90
	v_exp_f32_e32 v93, v93
	v_exp_f32_e32 v91, v91
	v_exp_f32_e32 v95, v95
	v_add_f32_e32 v94, v94, v218
	v_mul_f32_e32 v94, 0xbfb8aa3b, v94
	v_exp_f32_e32 v94, v94
	v_add_f32_e32 v88, 1.0, v88
	v_add_f32_e32 v92, 1.0, v92
	v_add_f32_e32 v89, 1.0, v89
	v_add_f32_e32 v90, 1.0, v90
	v_add_f32_e32 v93, 1.0, v93
	v_add_f32_e32 v91, 1.0, v91
	v_add_f32_e32 v95, 1.0, v95
	v_rcp_f32_e32 v100, v88
	v_rcp_f32_e32 v92, v92
	v_rcp_f32_e32 v101, v89
	v_rcp_f32_e32 v90, v90
	v_rcp_f32_e32 v88, v93
	v_rcp_f32_e32 v91, v91
	v_rcp_f32_e32 v93, v95
	v_add_f32_e32 v94, 1.0, v94
	v_rcp_f32_e32 v89, v94
	v_mul_f32_e64 v94, v100, -v220
	v_mul_f32_e32 v95, v92, v114
	v_mul_f32_e64 v92, v101, -v221
	v_mul_f32_e64 v90, v90, -v222
	v_mul_f32_e64 v91, v91, -v223
	v_mul_f32_e32 v96, v93, v115
	v_mul_f32_e32 v93, 0x3fb8aa3b, v94
	v_add_f32_e32 v94, v94, v94
	v_mul_f32_e32 v97, 0x3fb8aa3b, v92
	v_add_f32_e32 v92, v92, v92
	v_mul_f32_e32 v98, 0x3fb8aa3b, v90
	v_add_f32_e32 v90, v90, v90
	v_mul_f32_e32 v99, 0x3fb8aa3b, v91
	v_add_f32_e32 v91, v91, v91
	v_mul_f32_e32 v94, 0x3fb8aa3b, v94
	v_mul_f32_e32 v92, 0x3fb8aa3b, v92
	v_mul_f32_e32 v90, 0x3fb8aa3b, v90
	v_exp_f32_e32 v93, v93
	v_mul_f32_e32 v91, 0x3fb8aa3b, v91
	v_exp_f32_e32 v94, v94
	v_exp_f32_e32 v92, v92
	v_exp_f32_e32 v90, v90
	v_exp_f32_e32 v97, v97
	v_exp_f32_e32 v91, v91
	v_exp_f32_e32 v98, v98
	v_sub_f32_e32 v166, 1.0, v93
	v_sub_f32_e32 v93, 1.0, v94
	v_sub_f32_e32 v92, 1.0, v92
	v_sub_f32_e32 v94, 1.0, v90
	v_sub_f32_e32 v104, 1.0, v97
	v_sub_f32_e32 v97, 1.0, v91
	v_max_f32_e32 v93, 0, v93
	v_max_f32_e32 v92, 0, v92
	v_max_f32_e32 v94, 0, v94
	v_sub_f32_e32 v105, 1.0, v98
	v_max_f32_e32 v97, 0, v97
	v_sqrt_f32_e32 v98, v93
	v_sqrt_f32_e32 v92, v92
	v_sqrt_f32_e32 v93, v94
	v_exp_f32_e32 v99, v99
	v_sqrt_f32_e32 v94, v97
	v_pk_mul_f32 v[88:89], v[88:89], v[112:113]
	v_fma_mixlo_f16 v107, v95, v98, 0
	v_pk_mul_f32 v[88:89], v[88:89], v[92:93]
	v_sub_f32_e32 v106, 1.0, v99
	v_fma_mixlo_f16 v112, v96, v94, 0
	v_cvt_pk_f16_f32 v113, v88, v89
	v_cvt_pk_f16_f32 v91, v105, v106
	v_cvt_pk_f16_f32 v90, v166, v104
	v_pack_b32_f16 v88, v107, v113
	v_alignbit_b32 v89, v112, v113, 16
	global_store_dwordx2 v[110:111], v[90:91], off
	global_store_dwordx2 v[108:109], v[88:89], off
	s_nop 0
	v_lshlrev_b32_e32 v115, 3, v161
	v_lshlrev_b32_e32 v114, 3, v163
	v_add_u32_e32 v179, v125, v115
	v_add_u32_e32 v181, v125, v114
	v_lshlrev_b32_e32 v103, 3, v182
	v_lshlrev_b32_e32 v102, 3, v183
	v_lshlrev_b32_e32 v101, 3, v184
	v_add_u32_e32 v201, v125, v103
	v_add_u32_e32 v202, v125, v102
	v_add_u32_e32 v203, v125, v101
	v_lshlrev_b32_e32 v100, 3, v185
	v_add_u32_e32 v125, v125, v100
	v_add_f32_e32 v80, v80, v230
	v_add_f32_e32 v84, v84, v234
	v_add_f32_e32 v81, v81, v231
	v_add_f32_e32 v82, v82, v232
	v_add_f32_e32 v85, v85, v235
	v_add_f32_e32 v83, v83, v233
	v_add_f32_e32 v87, v87, v237
	v_mul_f32_e32 v80, 0xbfb8aa3b, v80
	v_mul_f32_e32 v84, 0xbfb8aa3b, v84
	v_mul_f32_e32 v81, 0xbfb8aa3b, v81
	v_mul_f32_e32 v82, 0xbfb8aa3b, v82
	v_mul_f32_e32 v85, 0xbfb8aa3b, v85
	v_mul_f32_e32 v83, 0xbfb8aa3b, v83
	v_mul_f32_e32 v87, 0xbfb8aa3b, v87
	v_exp_f32_e32 v80, v80
	v_exp_f32_e32 v84, v84
	v_exp_f32_e32 v81, v81
	v_exp_f32_e32 v82, v82
	v_exp_f32_e32 v85, v85
	v_exp_f32_e32 v83, v83
	v_exp_f32_e32 v87, v87
	v_add_f32_e32 v86, v86, v236
	v_mul_f32_e32 v86, 0xbfb8aa3b, v86
	v_exp_f32_e32 v86, v86
	v_add_f32_e32 v80, 1.0, v80
	v_add_f32_e32 v84, 1.0, v84
	v_add_f32_e32 v81, 1.0, v81
	v_add_f32_e32 v82, 1.0, v82
	v_add_f32_e32 v85, 1.0, v85
	v_add_f32_e32 v83, 1.0, v83
	v_add_f32_e32 v87, 1.0, v87
	v_rcp_f32_e32 v92, v80
	v_rcp_f32_e32 v84, v84
	v_rcp_f32_e32 v93, v81
	v_rcp_f32_e32 v82, v82
	v_rcp_f32_e32 v80, v85
	v_rcp_f32_e32 v83, v83
	v_rcp_f32_e32 v85, v87
	v_add_f32_e32 v86, 1.0, v86
	v_rcp_f32_e32 v81, v86
	v_mul_f32_e64 v86, v92, -v244
	v_mul_f32_e32 v87, v84, v167
	v_mul_f32_e64 v84, v93, -v245
	v_mul_f32_e64 v82, v82, -v246
	v_mul_f32_e64 v83, v83, -v247
	v_mul_f32_e32 v88, v85, v150
	v_mul_f32_e32 v85, 0x3fb8aa3b, v86
	v_add_f32_e32 v86, v86, v86
	v_mul_f32_e32 v89, 0x3fb8aa3b, v84
	v_add_f32_e32 v84, v84, v84
	v_mul_f32_e32 v90, 0x3fb8aa3b, v82
	v_add_f32_e32 v82, v82, v82
	v_mul_f32_e32 v91, 0x3fb8aa3b, v83
	v_add_f32_e32 v83, v83, v83
	v_mul_f32_e32 v86, 0x3fb8aa3b, v86
	v_mul_f32_e32 v84, 0x3fb8aa3b, v84
	v_mul_f32_e32 v82, 0x3fb8aa3b, v82
	v_exp_f32_e32 v85, v85
	v_mul_f32_e32 v83, 0x3fb8aa3b, v83
	v_exp_f32_e32 v86, v86
	v_exp_f32_e32 v84, v84
	v_exp_f32_e32 v82, v82
	v_exp_f32_e32 v89, v89
	v_exp_f32_e32 v83, v83
	v_exp_f32_e32 v90, v90
	v_sub_f32_e32 v98, 1.0, v85
	v_sub_f32_e32 v85, 1.0, v86
	v_sub_f32_e32 v84, 1.0, v84
	v_sub_f32_e32 v86, 1.0, v82
	v_exp_f32_e32 v91, v91
	v_sub_f32_e32 v96, 1.0, v89
	v_sub_f32_e32 v89, 1.0, v83
	v_max_f32_e32 v85, 0, v85
	v_max_f32_e32 v84, 0, v84
	v_max_f32_e32 v86, 0, v86
	v_sub_f32_e32 v94, 1.0, v90
	v_max_f32_e32 v89, 0, v89
	v_sqrt_f32_e32 v90, v85
	v_sqrt_f32_e32 v84, v84
	v_sqrt_f32_e32 v85, v86
	v_sqrt_f32_e32 v86, v89
	v_pk_mul_f32 v[80:81], v[80:81], v[168:169]
	v_sub_f32_e32 v95, 1.0, v91
	v_cvt_pk_f16_f32 v83, v94, v95
	v_cvt_pk_f16_f32 v82, v98, v96
	v_pk_mul_f32 v[80:81], v[80:81], v[84:85]
	global_store_dwordx2 v[110:111], v[82:83], off offset:32
	v_fma_mixlo_f16 v110, v87, v90, 0
	v_fma_mixlo_f16 v97, v88, v86, 0
	v_cvt_pk_f16_f32 v99, v80, v81
	v_pack_b32_f16 v80, v110, v99
	v_alignbit_b32 v81, v97, v99, 16
	global_store_dwordx2 v[108:109], v[80:81], off offset:32
	s_nop 0
	v_cvt_f16_f32_e32 v84, v151
	v_cvt_f32_f16_e32 v85, v196
	v_cvt_f32_f16_e32 v86, v197
	v_cvt_f32_f16_e32 v108, v198
	v_cvt_f32_f16_e32 v111, v84
	v_sub_f32_e32 v92, 1.0, v85
	v_sub_f32_e32 v150, 1.0, v86
	v_cvt_f32_f16_e32 v93, v195
	v_cvt_f32_f16_e32 v151, v199
	v_cvt_f32_f16_sdwa v169, v199 dst_sel:DWORD dst_unused:UNUSED_PAD src0_sel:WORD_1
	v_cvt_f32_f16_e32 v109, v200
	v_sub_f32_e32 v168, 1.0, v108
	v_sub_f32_e32 v108, 1.0, v111
	ds_write_b64 v186, v[92:93]
	ds_write_b64 v187, v[150:151]
	ds_write_b64 v188, v[168:169]
	ds_write_b64 v189, v[108:109]
	v_cvt_f16_f32_e32 v92, v128
	v_cvt_f16_f32_e32 v93, v129
	v_cvt_f16_f32_e32 v108, v130
	v_cvt_f16_f32_e32 v109, v131
	v_cvt_f32_f16_e32 v92, v92
	v_cvt_f32_f16_e32 v111, v93
	v_cvt_f32_f16_e32 v108, v108
	v_cvt_f32_f16_e32 v150, v109
	v_cvt_f32_f16_e32 v93, v176
	v_cvt_f32_f16_e32 v129, v177
	v_cvt_f32_f16_sdwa v131, v177 dst_sel:DWORD dst_unused:UNUSED_PAD src0_sel:WORD_1
	v_cvt_f32_f16_e32 v109, v180
	v_sub_f32_e32 v92, 1.0, v92
	v_sub_f32_e32 v128, 1.0, v111
	v_sub_f32_e32 v130, 1.0, v108
	v_sub_f32_e32 v108, 1.0, v150
	ds_write_b64 v190, v[92:93]
	ds_write_b64 v191, v[128:129]
	ds_write_b64 v192, v[130:131]
	ds_write_b64 v193, v[108:109]
	v_cvt_f16_f32_e32 v92, v116
	v_cvt_f16_f32_e32 v93, v117
	v_cvt_f16_f32_e32 v108, v118
	v_cvt_f16_f32_e32 v109, v119
	v_cvt_f32_f16_e32 v92, v92
	v_cvt_f32_f16_e32 v111, v93
	v_cvt_f32_f16_e32 v108, v108
	v_cvt_f32_f16_e32 v128, v109
	v_cvt_f32_f16_e32 v93, v120
	v_cvt_f32_f16_e32 v117, v121
	v_cvt_f32_f16_sdwa v119, v121 dst_sel:DWORD dst_unused:UNUSED_PAD src0_sel:WORD_1
	v_cvt_f32_f16_e32 v109, v122
	v_sub_f32_e32 v92, 1.0, v92
	v_sub_f32_e32 v116, 1.0, v111
	v_sub_f32_e32 v118, 1.0, v108
	v_sub_f32_e32 v108, 1.0, v128
	ds_write_b64 v175, v[92:93]
	ds_write_b64 v178, v[116:117]
	ds_write_b64 v179, v[118:119]
	ds_write_b64 v181, v[108:109]
	v_cvt_f16_f32_e32 v92, v170
	v_cvt_f16_f32_e32 v93, v171
	v_cvt_f16_f32_e32 v108, v172
	v_cvt_f16_f32_e32 v109, v173
	v_cvt_f32_f16_e32 v92, v92
	v_cvt_f32_f16_e32 v111, v93
	v_cvt_f32_f16_e32 v118, v108
	v_cvt_f32_f16_e32 v120, v109
	v_cvt_f32_f16_e32 v109, v126
	v_cvt_f32_f16_e32 v117, v127
	v_cvt_f32_f16_sdwa v119, v127 dst_sel:DWORD dst_unused:UNUSED_PAD src0_sel:WORD_1
	v_sub_f32_e32 v108, 1.0, v92
	v_sub_f32_e32 v116, 1.0, v111
	v_sub_f32_e32 v118, 1.0, v118
	ds_write_b64 v201, v[108:109]
	ds_write_b64 v202, v[116:117]
	ds_write_b64 v203, v[118:119]
	v_cvt_f16_f32_e32 v108, v166
	v_cvt_f32_f16_e32 v93, v174
	v_sub_f32_e32 v92, 1.0, v120
	ds_write_b64 v125, v[92:93]
	v_cvt_f16_f32_e32 v93, v105
	v_cvt_f16_f32_e32 v92, v104
	v_cvt_f16_f32_e32 v104, v106
	v_cvt_f32_f16_e32 v92, v92
	v_add_f32_e32 v73, v73, v213
	v_add_f32_e32 v72, v72, v212
	v_add_f32_e32 v76, v76, v216
	v_mul_f32_e32 v73, 0xbfb8aa3b, v73
	v_mul_f32_e32 v72, 0xbfb8aa3b, v72
	v_mul_f32_e32 v76, 0xbfb8aa3b, v76
	v_exp_f32_e32 v73, v73
	v_exp_f32_e32 v72, v72
	v_exp_f32_e32 v76, v76
	v_add_f32_e32 v74, v74, v214
	v_add_f32_e32 v73, 1.0, v73
	v_add_f32_e32 v72, 1.0, v72
	v_add_f32_e32 v76, 1.0, v76
	v_rcp_f32_e32 v73, v73
	v_rcp_f32_e32 v72, v72
	v_rcp_f32_e32 v76, v76
	v_mul_f32_e32 v74, 0xbfb8aa3b, v74
	v_mul_f32_e64 v73, v73, -v221
	v_add_f32_e32 v77, v77, v217
	v_mul_f32_e64 v72, v72, -v220
	v_mul_f32_e32 v81, v76, v149
	v_mul_f32_e32 v76, 0x3fb8aa3b, v73
	v_exp_f32_e32 v74, v74
	v_mul_f32_e32 v80, 0x3fb8aa3b, v72
	v_add_f32_e32 v72, v72, v72
	v_exp_f32_e32 v76, v76
	v_mul_f32_e32 v72, 0x3fb8aa3b, v72
	v_exp_f32_e32 v72, v72
	v_add_f32_e32 v73, v73, v73
	v_mul_f32_e32 v73, 0x3fb8aa3b, v73
	v_add_f32_e32 v74, 1.0, v74
	v_exp_f32_e32 v80, v80
	v_exp_f32_e32 v73, v73
	v_sub_f32_e32 v90, 1.0, v76
	v_rcp_f32_e32 v74, v74
	v_add_f32_e32 v76, v78, v218
	v_mul_f32_e32 v76, 0xbfb8aa3b, v76
	v_sub_f32_e32 v72, 1.0, v72
	v_exp_f32_e32 v76, v76
	v_max_f32_e32 v72, 0, v72
	v_sub_f32_e32 v109, 1.0, v80
	v_sqrt_f32_e32 v80, v72
	v_mul_f32_e32 v72, 0xbfb8aa3b, v77
	v_sub_f32_e32 v73, 1.0, v73
	v_mul_f32_e64 v77, v74, -v222
	v_max_f32_e32 v73, 0, v73
	v_mul_f32_e32 v74, 0x3fb8aa3b, v77
	v_exp_f32_e32 v78, v74
	v_sqrt_f32_e32 v74, v73
	v_add_f32_e32 v73, 1.0, v76
	v_add_f32_e32 v76, v77, v77
	v_add_f32_e32 v75, v75, v215
	v_mul_f32_e32 v76, 0x3fb8aa3b, v76
	v_mul_f32_e32 v75, 0xbfb8aa3b, v75
	v_exp_f32_e32 v76, v76
	v_exp_f32_e32 v77, v75
	v_sub_f32_e32 v111, 1.0, v78
	v_exp_f32_e32 v72, v72
	v_sub_f32_e32 v75, 1.0, v76
	v_add_f32_e32 v76, 1.0, v77
	v_rcp_f32_e32 v76, v76
	v_add_f32_e32 v77, v79, v219
	v_mul_f32_e32 v77, 0xbfb8aa3b, v77
	v_exp_f32_e32 v77, v77
	v_mul_f32_e64 v76, v76, -v223
	v_mul_f32_e32 v78, 0x3fb8aa3b, v76
	v_add_f32_e32 v76, v76, v76
	v_mul_f32_e32 v76, 0x3fb8aa3b, v76
	v_exp_f32_e32 v76, v76
	v_exp_f32_e32 v78, v78
	v_add_f32_e32 v77, 1.0, v77
	v_rcp_f32_e32 v77, v77
	v_add_f32_e32 v72, 1.0, v72
	v_rcp_f32_e32 v72, v72
	v_rcp_f32_e32 v73, v73
	v_max_f32_e32 v75, 0, v75
	v_sub_f32_e32 v76, 1.0, v76
	v_sqrt_f32_e32 v75, v75
	v_sub_f32_e32 v91, 1.0, v78
	v_max_f32_e32 v76, 0, v76
	v_sqrt_f32_e32 v78, v76
	v_mul_f32_e32 v79, v77, v148
	v_lshl_add_u64 v[86:87], s[18:19], 0, v[144:145]
	v_cvt_pk_f16_f32 v77, v111, v91
	v_cvt_pk_f16_f32 v76, v109, v90
	global_store_dwordx2 v[86:87], v[76:77], off
	v_and_b32_e32 v76, 0xffff0000, v146
	v_lshlrev_b32_e32 v77, 16, v147
	v_pk_mul_f32 v[72:73], v[72:73], v[76:77]
	v_fma_mixlo_f16 v116, v81, v80, 0
	v_pk_mul_f32 v[72:73], v[72:73], v[74:75]
	v_fma_mixlo_f16 v118, v79, v78, 0
	v_cvt_pk_f16_f32 v117, v72, v73
	v_lshl_add_u64 v[84:85], s[16:17], 0, v[144:145]
	v_pack_b32_f16 v72, v116, v117
	v_alignbit_b32 v73, v118, v117, 16
	global_store_dwordx2 v[84:85], v[72:73], off
	v_cvt_f32_f16_e32 v76, v108
	v_cvt_f32_f16_e32 v89, v107
	v_sub_f32_e32 v88, 1.0, v76
	v_lshlrev_b32_e32 v76, 8, v142
	v_and_b32_e32 v105, 0x2f00, v76
	v_add_u32_e32 v105, s26, v105
	v_add_u32_e32 v106, v105, v124
	ds_write_b64 v106, v[88:89]
	v_cvt_f32_f16_e32 v89, v113
	v_sub_f32_e32 v88, 1.0, v92
	v_cvt_f32_f16_e32 v92, v93
	v_add_u32_e32 v93, v105, v123
	ds_write_b64 v93, v[88:89]
	v_cvt_f32_f16_sdwa v89, v113 dst_sel:DWORD dst_unused:UNUSED_PAD src0_sel:WORD_1
	v_sub_f32_e32 v88, 1.0, v92
	v_cvt_f32_f16_e32 v92, v104
	v_add_u32_e32 v93, v105, v115
	ds_write_b64 v93, v[88:89]
	v_cvt_f32_f16_e32 v89, v112
	v_sub_f32_e32 v88, 1.0, v92
	v_cvt_f16_f32_e32 v92, v98
	v_add_u32_e32 v93, v105, v114
	ds_write_b64 v93, v[88:89]
	v_cvt_f16_f32_e32 v93, v96
	v_cvt_f32_f16_e32 v88, v92
	v_cvt_f32_f16_e32 v89, v110
	v_cvt_f16_f32_e32 v92, v94
	v_cvt_f16_f32_e32 v94, v95
	v_sub_f32_e32 v88, 1.0, v88
	v_cvt_f32_f16_e32 v93, v93
	v_add_u32_e32 v95, v105, v103
	ds_write_b64 v95, v[88:89]
	v_cvt_f32_f16_e32 v89, v99
	v_sub_f32_e32 v88, 1.0, v93
	v_cvt_f32_f16_e32 v92, v92
	v_add_u32_e32 v93, v105, v102
	ds_write_b64 v93, v[88:89]
	v_cvt_f32_f16_sdwa v89, v99 dst_sel:DWORD dst_unused:UNUSED_PAD src0_sel:WORD_1
	v_sub_f32_e32 v88, 1.0, v92
	v_add_u32_e32 v92, v105, v101
	v_cvt_f32_f16_e32 v93, v94
	ds_write_b64 v92, v[88:89]
	v_cvt_f32_f16_e32 v89, v97
	v_cvt_f16_f32_e32 v92, v109
	v_sub_f32_e32 v88, 1.0, v93
	v_add_u32_e32 v93, v105, v100
	ds_write_b64 v93, v[88:89]
	v_cvt_f32_f16_e32 v88, v92
	v_cvt_f16_f32_e32 v89, v90
	v_cvt_f16_f32_e32 v93, v91
	v_cvt_f32_f16_e32 v91, v116
	v_sub_f32_e32 v90, 1.0, v88
	v_lshlrev_b32_e32 v88, 8, v140
	v_and_b32_e32 v88, 0x3f00, v88
	v_add_u32_e32 v88, s26, v88
	v_cvt_f16_f32_e32 v92, v111
	v_cvt_f32_f16_e32 v89, v89
	v_add_u32_e32 v94, v88, v124
	ds_write_b64 v94, v[90:91]
	v_cvt_f32_f16_e32 v91, v117
	v_sub_f32_e32 v90, 1.0, v89
	v_add_u32_e32 v89, v88, v123
	v_cvt_f32_f16_e32 v92, v92
	ds_write_b64 v89, v[90:91]
	v_cvt_f32_f16_sdwa v91, v117 dst_sel:DWORD dst_unused:UNUSED_PAD src0_sel:WORD_1
	v_cvt_f32_f16_e32 v89, v93
	v_sub_f32_e32 v90, 1.0, v92
	v_add_u32_e32 v92, v88, v115
	ds_write_b64 v92, v[90:91]
	v_cvt_f32_f16_e32 v91, v118
	v_sub_f32_e32 v90, 1.0, v89
	v_add_u32_e32 v89, v88, v114
	ds_write_b64 v89, v[90:91]
	v_and_b32_e32 v89, 0xffff0000, v139
	v_add_f32_e32 v68, v68, v230
	v_mul_f32_e32 v68, 0xbfb8aa3b, v68
	v_exp_f32_e32 v68, v68
	v_add_f32_e32 v64, v64, v234
	v_mul_f32_e32 v64, 0xbfb8aa3b, v64
	v_exp_f32_e32 v64, v64
	v_add_f32_e32 v68, 1.0, v68
	v_rcp_f32_e32 v68, v68
	v_add_f32_e32 v65, v65, v235
	v_add_f32_e32 v64, 1.0, v64
	v_mul_f32_e32 v65, 0xbfb8aa3b, v65
	v_mul_f32_e64 v68, v68, -v244
	v_mul_f32_e32 v76, 0x3fb8aa3b, v68
	v_add_f32_e32 v68, v68, v68
	v_mul_f32_e32 v68, 0x3fb8aa3b, v68
	v_exp_f32_e32 v68, v68
	v_rcp_f32_e32 v64, v64
	v_exp_f32_e32 v65, v65
	v_lshlrev_b32_e32 v72, 16, v138
	v_sub_f32_e32 v68, 1.0, v68
	v_max_f32_e32 v68, 0, v68
	v_sqrt_f32_e32 v80, v68
	v_add_f32_e32 v68, v69, v231
	v_mul_f32_e32 v68, 0xbfb8aa3b, v68
	v_exp_f32_e32 v68, v68
	v_mul_f32_e32 v72, v64, v72
	v_add_f32_e32 v64, 1.0, v65
	v_add_f32_e32 v69, v70, v232
	v_add_f32_e32 v68, 1.0, v68
	v_rcp_f32_e32 v68, v68
	v_mul_f32_e32 v69, 0xbfb8aa3b, v69
	v_exp_f32_e32 v69, v69
	v_add_f32_e32 v71, v71, v233
	v_mul_f32_e64 v65, v68, -v245
	v_mul_f32_e32 v68, 0x3fb8aa3b, v65
	v_exp_f32_e32 v68, v68
	v_mul_f32_e32 v71, 0xbfb8aa3b, v71
	v_exp_f32_e32 v71, v71
	v_add_f32_e32 v65, v65, v65
	v_sub_f32_e32 v70, 1.0, v68
	v_add_f32_e32 v68, 1.0, v69
	v_rcp_f32_e32 v68, v68
	v_mul_f32_e32 v65, 0x3fb8aa3b, v65
	v_exp_f32_e32 v65, v65
	v_add_f32_e32 v66, v66, v236
	v_mul_f32_e64 v69, v68, -v246
	v_add_f32_e32 v71, 1.0, v71
	v_mul_f32_e32 v66, 0xbfb8aa3b, v66
	v_mul_f32_e32 v68, 0x3fb8aa3b, v69
	v_rcp_f32_e32 v71, v71
	v_exp_f32_e32 v66, v66
	v_exp_f32_e32 v73, v68
	v_add_f32_e32 v67, v67, v237
	v_sub_f32_e32 v65, 1.0, v65
	v_mul_f32_e32 v67, 0xbfb8aa3b, v67
	v_max_f32_e32 v65, 0, v65
	v_add_f32_e32 v69, v69, v69
	v_exp_f32_e32 v67, v67
	v_mul_f32_e64 v71, v71, -v247
	v_sqrt_f32_e32 v68, v65
	v_add_f32_e32 v65, 1.0, v66
	v_sub_f32_e32 v66, 1.0, v73
	v_mul_f32_e32 v69, 0x3fb8aa3b, v69
	v_mul_f32_e32 v73, 0x3fb8aa3b, v71
	v_add_f32_e32 v71, v71, v71
	v_exp_f32_e32 v69, v69
	v_mul_f32_e32 v71, 0x3fb8aa3b, v71
	v_exp_f32_e32 v71, v71
	v_exp_f32_e32 v76, v76
	v_exp_f32_e32 v73, v73
	v_add_f32_e32 v67, 1.0, v67
	v_rcp_f32_e32 v67, v67
	v_sub_f32_e32 v69, 1.0, v69
	v_rcp_f32_e32 v64, v64
	v_rcp_f32_e32 v65, v65
	v_max_f32_e32 v69, 0, v69
	v_sub_f32_e32 v71, 1.0, v71
	v_sub_f32_e32 v76, 1.0, v76
	v_sqrt_f32_e32 v69, v69
	v_sub_f32_e32 v73, 1.0, v73
	v_max_f32_e32 v71, 0, v71
	v_sqrt_f32_e32 v71, v71
	v_mul_f32_e32 v74, v67, v89
	v_cvt_f16_f32_e32 v78, v66
	v_cvt_pk_f16_f32 v67, v66, v73
	v_cvt_pk_f16_f32 v66, v76, v70
	v_cvt_f16_f32_e32 v75, v76
	global_store_dwordx2 v[86:87], v[66:67], off offset:32
	v_and_b32_e32 v66, 0xffff0000, v138
	v_lshlrev_b32_e32 v67, 16, v139
	v_pk_mul_f32 v[64:65], v[64:65], v[66:67]
	v_cvt_f16_f32_e32 v77, v70
	v_pk_mul_f32 v[64:65], v[64:65], v[68:69]
	v_fma_mixlo_f16 v70, v72, v80, 0
	v_cvt_pk_f16_f32 v66, v64, v65
	v_fma_mixlo_f16 v67, v74, v71, 0
	v_pack_b32_f16 v64, v70, v66
	v_cvt_f32_f16_e32 v68, v75
	v_alignbit_b32 v65, v67, v66, 16
	global_store_dwordx2 v[84:85], v[64:65], off offset:32
	v_cvt_f32_f16_e32 v65, v70
	v_sub_f32_e32 v64, 1.0, v68
	v_add_u32_e32 v68, v88, v103
	v_cvt_f32_f16_e32 v69, v77
	v_cvt_f16_f32_e32 v79, v73
	ds_write_b64 v68, v[64:65]
	v_cvt_f32_f16_e32 v65, v66
	v_cvt_f32_f16_e32 v68, v78
	v_sub_f32_e32 v64, 1.0, v69
	v_add_u32_e32 v69, v88, v102
	ds_write_b64 v69, v[64:65]
	v_cvt_f32_f16_sdwa v65, v66 dst_sel:DWORD dst_unused:UNUSED_PAD src0_sel:WORD_1
	v_cvt_f32_f16_e32 v66, v79
	v_cvt_f32_f16_e32 v67, v67
	v_sub_f32_e32 v64, 1.0, v68
	v_add_u32_e32 v68, v88, v101
	ds_write_b64 v68, v[64:65]
	v_sub_f32_e32 v66, 1.0, v66
	v_add_u32_e32 v64, v88, v100
	ds_write_b64 v64, v[66:67]
	s_waitcnt lgkmcnt(0)
	s_and_saveexec_b64 s[2:3], s[4:5]
	s_cbranch_execz .LBB0_1222
	s_ashr_i32 s10, s31, 6
	s_mov_b32 s11, 0
	v_mov_b32_e32 v65, 0
	v_mov_b32_e32 v66, 1.0
	s_mov_b32 s12, 48

.LBB0_2040:
	s_andn2_b64 vcc, exec, s[0:1]
	s_cbranch_vccnz .LBB0_2977
	s_cmp_lt_i32 s79, 2
	s_mov_b64 s[0:1], -1
	s_cbranch_scc1 .LBB0_2072
	s_cmp_gt_i32 s79, 2
	s_cbranch_scc0 .LBB0_2055
	s_add_i32 s0, s91, 0x20098
	v_mov_b32_e32 v0, s0
	s_add_i32 s0, s91, 0x2009c
	v_mov_b32_e32 v1, s0
	s_add_i32 s0, s91, 0x200b0
	v_mov_b32_e32 v2, s0
	s_add_i32 s0, s91, 0x200b4
	v_mov_b32_e32 v3, s0
	ds_read_b32 v0, v0
	ds_read_b32 v1, v1
	ds_read_b32 v2, v2
	ds_read_b32 v3, v3
	v_readlane_b32 s0, v254, 20
	s_waitcnt lgkmcnt(0)
	v_readfirstlane_b32 s2, v0
	v_readfirstlane_b32 s3, v1
	v_readfirstlane_b32 s8, v2
	v_readfirstlane_b32 s9, v3
	s_cmpk_gt_i32 s0, 0x41ff
	v_and_b32_e32 v134, 15, v162
	v_readlane_b32 s1, v254, 21
	s_cbranch_scc1 .LBB0_2048
	v_readlane_b32 s0, v254, 26
	v_readlane_b32 s14, v254, 20
	s_lshl_b32 s4, s0, 11
	s_ashr_i32 s0, s14, 31
	s_lshr_b32 s0, s0, 26
	s_add_i32 s0, s14, s0
	s_and_b32 s1, s0, 0xffffffc0
	s_sub_i32 s5, s14, s1
	s_lshr_b32 s0, s5, 4
	s_bfe_i32 s6, s0, 0x80000
	s_bfe_u32 s6, s6, 0x2000d
	s_add_i32 s6, s0, s6
	s_and_b32 s6, s6, 0xfc
	s_sub_i32 s0, s0, s6
	s_sext_i32_i8 s0, s0
	s_lshl_b32 s0, s0, 6
	v_or_b32_e32 v8, s1, v134
	s_ashr_i32 s1, s0, 31
	s_lshl_b64 s[0:1], s[0:1], 1
	v_readlane_b32 s6, v254, 34
	v_readlane_b32 s7, v254, 35
	s_add_u32 s0, s6, s0
	s_addc_u32 s1, s7, s1
	v_and_b32_e32 v152, 48, v164
	v_lshl_add_u64 v[0:1], s[0:1], 0, v[152:153]
	v_readlane_b32 s0, v254, 32
	v_lshl_or_b32 v2, s5, 6, v134
	v_readlane_b32 s1, v254, 33
	v_ashrrev_i32_e32 v3, 31, v2
	v_lshrrev_b32_e32 v64, 2, v164
	v_lshl_add_u64 v[4:5], s[0:1], 0, v[152:153]
	s_mov_b64 s[0:1], 0x14980000
	v_lshl_add_u64 v[128:129], v[4:5], 0, s[0:1]
	v_lshlrev_b64 v[4:5], 7, v[2:3]
	v_or_b32_e32 v3, 16, v8
	s_waitcnt vmcnt(0)
	v_mad_i64_i32 v[12:13], s[0:1], v3, s95, v[0:1]
	v_or_b32_e32 v3, 32, v8
	v_mad_i64_i32 v[20:21], s[0:1], v3, s95, v[0:1]
	v_or_b32_e32 v3, 48, v8
	v_mad_i64_i32 v[6:7], s[0:1], v8, s95, v[0:1]
	v_mad_i64_i32 v[28:29], s[0:1], v3, s95, v[0:1]
	v_or_b32_e32 v0, 16, v2
	v_ashrrev_i32_e32 v1, 31, v0
	v_lshlrev_b64 v[0:1], 7, v[0:1]
	v_lshl_add_u64 v[44:45], v[128:129], 0, v[0:1]
	v_or_b32_e32 v0, 32, v2
	v_ashrrev_i32_e32 v1, 31, v0
	v_lshlrev_b64 v[0:1], 7, v[0:1]
	v_lshl_add_u64 v[52:53], v[128:129], 0, v[0:1]
	v_or_b32_e32 v0, 48, v2
	v_ashrrev_i32_e32 v1, 31, v0
	v_lshlrev_b64 v[0:1], 7, v[0:1]
	v_lshl_add_u64 v[36:37], v[128:129], 0, v[4:5]
	v_lshl_add_u64 v[60:61], v[128:129], 0, v[0:1]
	global_load_dwordx4 v[0:3], v[6:7], off
	s_nop 0
	global_load_dwordx4 v[4:7], v[6:7], off offset:64
	s_nop 0
	global_load_dwordx4 v[8:11], v[12:13], off
	s_nop 0
	global_load_dwordx4 v[12:15], v[12:13], off offset:64
	s_nop 0
	global_load_dwordx4 v[16:19], v[20:21], off
	s_nop 0
	global_load_dwordx4 v[20:23], v[20:21], off offset:64
	s_nop 0
	global_load_dwordx4 v[24:27], v[28:29], off
	s_nop 0
	global_load_dwordx4 v[28:31], v[28:29], off offset:64
	s_nop 0
	global_load_dwordx4 v[32:35], v[36:37], off
	s_nop 0
	global_load_dwordx4 v[36:39], v[36:37], off offset:64
	s_nop 0
	global_load_dwordx4 v[40:43], v[44:45], off
	s_nop 0
	global_load_dwordx4 v[44:47], v[44:45], off offset:64
	s_nop 0
	global_load_dwordx4 v[48:51], v[52:53], off
	s_nop 0
	global_load_dwordx4 v[52:55], v[52:53], off offset:64
	s_nop 0
	global_load_dwordx4 v[56:59], v[60:61], off
	s_nop 0
	global_load_dwordx4 v[60:63], v[60:61], off offset:64
	v_readlane_b32 s0, v254, 22
	s_lshl_b32 s11, s0, 6
	v_lshl_add_u64 v[130:131], s[6:7], 0, v[152:153]
	v_and_b32_e32 v135, 12, v64
	s_lshl_b32 s10, s14, 6
	v_or_b32_e32 v136, s11, v134
	s_lshl_b32 s12, s4, 2
	s_mov_b32 s4, s14
	v_readlane_b32 s15, v254, 21
	v_readlane_b32 s1, v254, 23
	s_waitcnt vmcnt(0)
	s_branch .LBB0_2046
.LBB0_2045:
	s_ashr_i32 s5, s4, 31
	s_lshr_b32 s5, s5, 26
	s_add_i32 s5, s4, s5
	s_andn2_b32 s5, s5, 63
	s_sub_i32 s4, s4, s5
	s_ashr_i32 s14, s4, 4
	v_or_b32_e32 v132, s5, v134
	s_cmp_eq_u32 s14, 2
	s_mov_b32 s5, 0x8400000
	s_cselect_b32 s5, 0x4200000, s5
	s_cmp_lg_u32 s14, 1
	s_cselect_b32 s5, s5, 0x6300000
	s_cmp_gt_u32 s4, 15
	s_cselect_b32 s4, s5, 0x2100000
	s_and_b32 s5, s10, 0x3c0
	v_readlane_b32 s6, v254, 32
	v_readlane_b32 s7, v254, 33
	s_add_u32 s6, s6, s4
	s_addc_u32 s7, s7, 0
	s_cmp_lt_i32 s14, 2
	s_cselect_b64 vcc, -1, 0
	v_or_b32_e32 v137, s5, v135
	s_and_b64 s[4:5], vcc, exec
	s_cselect_b32 s5, s2, s8
	s_cselect_b32 s4, s3, s9
	s_add_u32 s5, s5, s12
	s_addc_u32 s15, s4, 0
	s_lshl_b32 s4, s14, 12
	s_and_b32 s4, s4, 0x1000
	v_ashrrev_i32_e32 v133, 31, v132
	s_add_u32 s4, s5, s4
	v_lshlrev_b64 v[138:139], 11, v[132:133]
	s_addc_u32 s5, s15, 0
	v_lshlrev_b32_e32 v133, 2, v137
	v_lshl_add_u64 v[142:143], s[6:7], 0, v[138:139]
	v_lshlrev_b32_e32 v152, 1, v137
	s_add_i32 s10, s10, s11
	v_add_f32_e32 v124, v124, v188
	v_mul_f32_e32 v124, 0xbfb8aa3b, v124
	v_exp_f32_e32 v124, v124
	s_nop 0
	v_add_f32_e32 v124, 1.0, v124
	v_rcp_f32_e32 v124, v124
	s_nop 0
	v_mul_f32_e32 v138, 0xbf1b4598, v124
	v_mul_f32_e32 v138, 0x3fb8aa3b, v138
	v_exp_f32_e32 v138, v138
	s_nop 0
	v_sub_f32_e32 v138, 1.0, v138
	v_cndmask_b32_e32 v138, v124, v138, vcc
	v_add_f32_e32 v124, v125, v189
	v_mul_f32_e32 v124, 0xbfb8aa3b, v124
	v_exp_f32_e32 v124, v124
	s_nop 0
	v_add_f32_e32 v124, 1.0, v124
	v_rcp_f32_e32 v124, v124
	s_nop 0
	v_mul_f32_e32 v125, 0xbf1b4598, v124
	v_mul_f32_e32 v125, 0x3fb8aa3b, v125
	v_exp_f32_e32 v125, v125
	s_nop 0
	v_sub_f32_e32 v125, 1.0, v125
	v_cndmask_b32_e32 v139, v124, v125, vcc
	v_add_f32_e32 v124, v126, v190
	v_mul_f32_e32 v124, 0xbfb8aa3b, v124
	v_exp_f32_e32 v124, v124
	s_nop 0
	v_add_f32_e32 v124, 1.0, v124
	v_rcp_f32_e32 v124, v124
	s_nop 0
	v_mul_f32_e32 v125, 0xbf1b4598, v124
	v_mul_f32_e32 v125, 0x3fb8aa3b, v125
	v_exp_f32_e32 v125, v125
	s_nop 0
	v_sub_f32_e32 v125, 1.0, v125
	v_cndmask_b32_e32 v126, v124, v125, vcc
	v_add_f32_e32 v124, v127, v191
	v_mul_f32_e32 v124, 0xbfb8aa3b, v124
	v_exp_f32_e32 v124, v124
	s_nop 0
	v_add_f32_e32 v124, 1.0, v124
	v_rcp_f32_e32 v124, v124
	s_nop 0
	v_mul_f32_e32 v125, 0xbf1b4598, v124
	v_mul_f32_e32 v125, 0x3fb8aa3b, v125
	v_exp_f32_e32 v125, v125
	s_nop 0
	v_sub_f32_e32 v125, 1.0, v125
	v_cndmask_b32_e32 v127, v124, v125, vcc
	v_lshl_add_u64 v[124:125], v[142:143], 0, v[152:153]
	v_cvt_pk_f16_f32 v127, v126, v127
	v_cvt_pk_f16_f32 v126, v138, v139
	global_store_dwordx2 v[124:125], v[126:127], off
	v_add_f32_e32 v120, v120, v192
	v_mul_f32_e32 v120, 0xbfb8aa3b, v120
	v_exp_f32_e32 v120, v120
	v_add_f32_e32 v121, v121, v193
	v_mul_f32_e32 v121, 0xbfb8aa3b, v121
	v_exp_f32_e32 v121, v121
	v_add_f32_e32 v120, 1.0, v120
	v_rcp_f32_e32 v120, v120
	v_add_f32_e32 v121, 1.0, v121
	v_rcp_f32_e32 v121, v121
	v_mul_f32_e32 v126, 0xbf1b4598, v120
	v_mul_f32_e32 v126, 0x3fb8aa3b, v126
	v_exp_f32_e32 v126, v126
	s_nop 0
	v_sub_f32_e32 v126, 1.0, v126
	v_cndmask_b32_e32 v120, v120, v126, vcc
	v_mul_f32_e32 v126, 0xbf1b4598, v121
	v_mul_f32_e32 v126, 0x3fb8aa3b, v126
	v_exp_f32_e32 v126, v126
	s_nop 0
	v_sub_f32_e32 v126, 1.0, v126
	v_cndmask_b32_e32 v126, v121, v126, vcc
	v_add_f32_e32 v121, v122, v194
	v_mul_f32_e32 v121, 0xbfb8aa3b, v121
	v_exp_f32_e32 v121, v121
	v_cvt_pk_f16_f32 v120, v120, v126
	v_add_f32_e32 v121, 1.0, v121
	v_rcp_f32_e32 v121, v121
	s_nop 0
	v_mul_f32_e32 v122, 0xbf1b4598, v121
	v_mul_f32_e32 v122, 0x3fb8aa3b, v122
	v_exp_f32_e32 v122, v122
	s_nop 0
	v_sub_f32_e32 v122, 1.0, v122
	v_cndmask_b32_e32 v121, v121, v122, vcc
	v_add_f32_e32 v122, v123, v195
	v_mul_f32_e32 v122, 0xbfb8aa3b, v122
	v_exp_f32_e32 v122, v122
	s_nop 0
	v_add_f32_e32 v122, 1.0, v122
	v_rcp_f32_e32 v122, v122
	s_nop 0
	v_mul_f32_e32 v123, 0xbf1b4598, v122
	v_mul_f32_e32 v123, 0x3fb8aa3b, v123
	v_exp_f32_e32 v123, v123
	s_nop 0
	v_sub_f32_e32 v123, 1.0, v123
	v_cndmask_b32_e32 v122, v122, v123, vcc
	v_cvt_pk_f16_f32 v121, v121, v122
	global_store_dwordx2 v[124:125], v[120:121], off offset:32
	v_add_f32_e32 v116, v116, v196
	v_mul_f32_e32 v116, 0xbfb8aa3b, v116
	v_exp_f32_e32 v116, v116
	v_add_f32_e32 v117, v117, v197
	v_mul_f32_e32 v117, 0xbfb8aa3b, v117
	v_exp_f32_e32 v117, v117
	v_add_f32_e32 v116, 1.0, v116
	v_rcp_f32_e32 v116, v116
	v_add_f32_e32 v117, 1.0, v117
	v_rcp_f32_e32 v117, v117
	v_mul_f32_e32 v120, 0xbf1b4598, v116
	v_mul_f32_e32 v120, 0x3fb8aa3b, v120
	v_exp_f32_e32 v120, v120
	s_nop 0
	v_sub_f32_e32 v120, 1.0, v120
	v_cndmask_b32_e32 v116, v116, v120, vcc
	v_mul_f32_e32 v120, 0xbf1b4598, v117
	v_mul_f32_e32 v120, 0x3fb8aa3b, v120
	v_exp_f32_e32 v120, v120
	s_nop 0
	v_sub_f32_e32 v120, 1.0, v120
	v_cndmask_b32_e32 v120, v117, v120, vcc
	v_add_f32_e32 v117, v118, v198
	v_mul_f32_e32 v117, 0xbfb8aa3b, v117
	v_exp_f32_e32 v117, v117
	v_cvt_pk_f16_f32 v116, v116, v120
	v_add_f32_e32 v117, 1.0, v117
	v_rcp_f32_e32 v117, v117
	s_nop 0
	v_mul_f32_e32 v118, 0xbf1b4598, v117
	v_mul_f32_e32 v118, 0x3fb8aa3b, v118
	v_exp_f32_e32 v118, v118
	s_nop 0
	v_sub_f32_e32 v118, 1.0, v118
	v_cndmask_b32_e32 v117, v117, v118, vcc
	v_add_f32_e32 v118, v119, v199
	v_mul_f32_e32 v118, 0xbfb8aa3b, v118
	v_exp_f32_e32 v118, v118
	s_nop 0
	v_add_f32_e32 v118, 1.0, v118
	v_rcp_f32_e32 v118, v118
	s_nop 0
	v_mul_f32_e32 v119, 0xbf1b4598, v118
	v_mul_f32_e32 v119, 0x3fb8aa3b, v119
	v_exp_f32_e32 v119, v119
	s_nop 0
	v_sub_f32_e32 v119, 1.0, v119
	v_cndmask_b32_e32 v118, v118, v119, vcc
	v_cvt_pk_f16_f32 v117, v117, v118
	global_store_dwordx2 v[124:125], v[116:117], off offset:64
	v_add_f32_e32 v112, v112, v200
	v_mul_f32_e32 v112, 0xbfb8aa3b, v112
	v_exp_f32_e32 v112, v112
	v_add_f32_e32 v113, v113, v201
	v_mul_f32_e32 v113, 0xbfb8aa3b, v113
	v_exp_f32_e32 v113, v113
	v_add_f32_e32 v112, 1.0, v112
	v_rcp_f32_e32 v112, v112
	v_add_f32_e32 v113, 1.0, v113
	v_rcp_f32_e32 v113, v113
	v_mul_f32_e32 v116, 0xbf1b4598, v112
	v_mul_f32_e32 v116, 0x3fb8aa3b, v116
	v_exp_f32_e32 v116, v116
	s_nop 0
	v_sub_f32_e32 v116, 1.0, v116
	v_cndmask_b32_e32 v112, v112, v116, vcc
	v_mul_f32_e32 v116, 0xbf1b4598, v113
	v_mul_f32_e32 v116, 0x3fb8aa3b, v116
	v_exp_f32_e32 v116, v116
	s_nop 0
	v_sub_f32_e32 v116, 1.0, v116
	v_cndmask_b32_e32 v116, v113, v116, vcc
	v_add_f32_e32 v113, v114, v202
	v_mul_f32_e32 v113, 0xbfb8aa3b, v113
	v_exp_f32_e32 v113, v113
	v_cvt_pk_f16_f32 v112, v112, v116
	v_add_f32_e32 v113, 1.0, v113
	v_rcp_f32_e32 v113, v113
	s_nop 0
	v_mul_f32_e32 v114, 0xbf1b4598, v113
	v_mul_f32_e32 v114, 0x3fb8aa3b, v114
	v_exp_f32_e32 v114, v114
	s_nop 0
	v_sub_f32_e32 v114, 1.0, v114
	v_cndmask_b32_e32 v113, v113, v114, vcc
	v_add_f32_e32 v114, v115, v203
	v_mul_f32_e32 v114, 0xbfb8aa3b, v114
	v_exp_f32_e32 v114, v114
	s_nop 0
	v_add_f32_e32 v114, 1.0, v114
	v_rcp_f32_e32 v114, v114
	s_nop 0
	v_mul_f32_e32 v115, 0xbf1b4598, v114
	v_mul_f32_e32 v115, 0x3fb8aa3b, v115
	v_exp_f32_e32 v115, v115
	s_nop 0
	v_sub_f32_e32 v115, 1.0, v115
	v_cndmask_b32_e32 v114, v114, v115, vcc
	v_cvt_pk_f16_f32 v113, v113, v114
	global_store_dwordx2 v[124:125], v[112:113], off offset:96
	v_or_b32_e32 v112, 16, v132
	v_ashrrev_i32_e32 v113, 31, v112
	v_lshlrev_b64 v[112:113], 11, v[112:113]
	v_lshl_add_u64 v[116:117], s[6:7], 0, v[112:113]
	v_add_f32_e32 v108, v108, v188
	v_mul_f32_e32 v108, 0xbfb8aa3b, v108
	v_exp_f32_e32 v108, v108
	s_nop 0
	v_add_f32_e32 v108, 1.0, v108
	v_rcp_f32_e32 v108, v108
	s_nop 0
	v_mul_f32_e32 v112, 0xbf1b4598, v108
	v_mul_f32_e32 v112, 0x3fb8aa3b, v112
	v_exp_f32_e32 v112, v112
	s_nop 0
	v_sub_f32_e32 v112, 1.0, v112
	v_cndmask_b32_e32 v112, v108, v112, vcc
	v_add_f32_e32 v108, v109, v189
	v_mul_f32_e32 v108, 0xbfb8aa3b, v108
	v_exp_f32_e32 v108, v108
	s_nop 0
	v_add_f32_e32 v108, 1.0, v108
	v_rcp_f32_e32 v108, v108
	s_nop 0
	v_mul_f32_e32 v109, 0xbf1b4598, v108
	v_mul_f32_e32 v109, 0x3fb8aa3b, v109
	v_exp_f32_e32 v109, v109
	s_nop 0
	v_sub_f32_e32 v109, 1.0, v109
	v_cndmask_b32_e32 v113, v108, v109, vcc
	v_add_f32_e32 v108, v110, v190
	v_mul_f32_e32 v108, 0xbfb8aa3b, v108
	v_exp_f32_e32 v108, v108
	s_nop 0
	v_add_f32_e32 v108, 1.0, v108
	v_rcp_f32_e32 v108, v108
	s_nop 0
	v_mul_f32_e32 v109, 0xbf1b4598, v108
	v_mul_f32_e32 v109, 0x3fb8aa3b, v109
	v_exp_f32_e32 v109, v109
	s_nop 0
	v_sub_f32_e32 v109, 1.0, v109
	v_cndmask_b32_e32 v110, v108, v109, vcc
	v_add_f32_e32 v108, v111, v191
	v_mul_f32_e32 v108, 0xbfb8aa3b, v108
	v_exp_f32_e32 v108, v108
	s_nop 0
	v_add_f32_e32 v108, 1.0, v108
	v_rcp_f32_e32 v108, v108
	s_nop 0
	v_mul_f32_e32 v109, 0xbf1b4598, v108
	v_mul_f32_e32 v109, 0x3fb8aa3b, v109
	v_exp_f32_e32 v109, v109
	s_nop 0
	v_sub_f32_e32 v109, 1.0, v109
	v_cndmask_b32_e32 v111, v108, v109, vcc
	v_lshl_add_u64 v[108:109], v[116:117], 0, v[152:153]
	v_cvt_pk_f16_f32 v111, v110, v111
	v_cvt_pk_f16_f32 v110, v112, v113
	global_store_dwordx2 v[108:109], v[110:111], off
	v_add_f32_e32 v104, v104, v192
	v_mul_f32_e32 v104, 0xbfb8aa3b, v104
	v_exp_f32_e32 v104, v104
	v_add_f32_e32 v105, v105, v193
	v_mul_f32_e32 v105, 0xbfb8aa3b, v105
	v_exp_f32_e32 v105, v105
	v_add_f32_e32 v104, 1.0, v104
	v_rcp_f32_e32 v104, v104
	v_add_f32_e32 v105, 1.0, v105
	v_rcp_f32_e32 v105, v105
	v_mul_f32_e32 v110, 0xbf1b4598, v104
	v_mul_f32_e32 v110, 0x3fb8aa3b, v110
	v_exp_f32_e32 v110, v110
	s_nop 0
	v_sub_f32_e32 v110, 1.0, v110
	v_cndmask_b32_e32 v104, v104, v110, vcc
	v_mul_f32_e32 v110, 0xbf1b4598, v105
	v_mul_f32_e32 v110, 0x3fb8aa3b, v110
	v_exp_f32_e32 v110, v110
	s_nop 0
	v_sub_f32_e32 v110, 1.0, v110
	v_cndmask_b32_e32 v110, v105, v110, vcc
	v_add_f32_e32 v105, v106, v194
	v_mul_f32_e32 v105, 0xbfb8aa3b, v105
	v_exp_f32_e32 v105, v105
	v_cvt_pk_f16_f32 v104, v104, v110
	v_add_f32_e32 v105, 1.0, v105
	v_rcp_f32_e32 v105, v105
	s_nop 0
	v_mul_f32_e32 v106, 0xbf1b4598, v105
	v_mul_f32_e32 v106, 0x3fb8aa3b, v106
	v_exp_f32_e32 v106, v106
	s_nop 0
	v_sub_f32_e32 v106, 1.0, v106
	v_cndmask_b32_e32 v105, v105, v106, vcc
	v_add_f32_e32 v106, v107, v195
	v_mul_f32_e32 v106, 0xbfb8aa3b, v106
	v_exp_f32_e32 v106, v106
	s_nop 0
	v_add_f32_e32 v106, 1.0, v106
	v_rcp_f32_e32 v106, v106
	s_nop 0
	v_mul_f32_e32 v107, 0xbf1b4598, v106
	v_mul_f32_e32 v107, 0x3fb8aa3b, v107
	v_exp_f32_e32 v107, v107
	s_nop 0
	v_sub_f32_e32 v107, 1.0, v107
	v_cndmask_b32_e32 v106, v106, v107, vcc
	v_cvt_pk_f16_f32 v105, v105, v106
	global_store_dwordx2 v[108:109], v[104:105], off offset:32
	v_add_f32_e32 v100, v100, v196
	v_mul_f32_e32 v100, 0xbfb8aa3b, v100
	v_exp_f32_e32 v100, v100
	v_add_f32_e32 v101, v101, v197
	v_mul_f32_e32 v101, 0xbfb8aa3b, v101
	v_exp_f32_e32 v101, v101
	v_add_f32_e32 v100, 1.0, v100
	v_rcp_f32_e32 v100, v100
	v_add_f32_e32 v101, 1.0, v101
	v_rcp_f32_e32 v101, v101
	v_mul_f32_e32 v104, 0xbf1b4598, v100
	v_mul_f32_e32 v104, 0x3fb8aa3b, v104
	v_exp_f32_e32 v104, v104
	s_nop 0
	v_sub_f32_e32 v104, 1.0, v104
	v_cndmask_b32_e32 v100, v100, v104, vcc
	v_mul_f32_e32 v104, 0xbf1b4598, v101
	v_mul_f32_e32 v104, 0x3fb8aa3b, v104
	v_exp_f32_e32 v104, v104
	s_nop 0
	v_sub_f32_e32 v104, 1.0, v104
	v_cndmask_b32_e32 v104, v101, v104, vcc
	v_add_f32_e32 v101, v102, v198
	v_mul_f32_e32 v101, 0xbfb8aa3b, v101
	v_exp_f32_e32 v101, v101
	v_cvt_pk_f16_f32 v100, v100, v104
	v_add_f32_e32 v101, 1.0, v101
	v_rcp_f32_e32 v101, v101
	s_nop 0
	v_mul_f32_e32 v102, 0xbf1b4598, v101
	v_mul_f32_e32 v102, 0x3fb8aa3b, v102
	v_exp_f32_e32 v102, v102
	s_nop 0
	v_sub_f32_e32 v102, 1.0, v102
	v_cndmask_b32_e32 v101, v101, v102, vcc
	v_add_f32_e32 v102, v103, v199
	v_mul_f32_e32 v102, 0xbfb8aa3b, v102
	v_exp_f32_e32 v102, v102
	s_nop 0
	v_add_f32_e32 v102, 1.0, v102
	v_rcp_f32_e32 v102, v102
	s_nop 0
	v_mul_f32_e32 v103, 0xbf1b4598, v102
	v_mul_f32_e32 v103, 0x3fb8aa3b, v103
	v_exp_f32_e32 v103, v103
	s_nop 0
	v_sub_f32_e32 v103, 1.0, v103
	v_cndmask_b32_e32 v102, v102, v103, vcc
	v_cvt_pk_f16_f32 v101, v101, v102
	global_store_dwordx2 v[108:109], v[100:101], off offset:64
	v_add_f32_e32 v96, v96, v200
	v_mul_f32_e32 v96, 0xbfb8aa3b, v96
	v_exp_f32_e32 v96, v96
	v_add_f32_e32 v97, v97, v201
	v_mul_f32_e32 v97, 0xbfb8aa3b, v97
	v_exp_f32_e32 v97, v97
	v_add_f32_e32 v96, 1.0, v96
	v_rcp_f32_e32 v96, v96
	v_add_f32_e32 v97, 1.0, v97
	v_rcp_f32_e32 v97, v97
	v_mul_f32_e32 v100, 0xbf1b4598, v96
	v_mul_f32_e32 v100, 0x3fb8aa3b, v100
	v_exp_f32_e32 v100, v100
	s_nop 0
	v_sub_f32_e32 v100, 1.0, v100
	v_cndmask_b32_e32 v96, v96, v100, vcc
	v_mul_f32_e32 v100, 0xbf1b4598, v97
	v_mul_f32_e32 v100, 0x3fb8aa3b, v100
	v_exp_f32_e32 v100, v100
	s_nop 0
	v_sub_f32_e32 v100, 1.0, v100
	v_cndmask_b32_e32 v100, v97, v100, vcc
	v_add_f32_e32 v97, v98, v202
	v_mul_f32_e32 v97, 0xbfb8aa3b, v97
	v_exp_f32_e32 v97, v97
	v_cvt_pk_f16_f32 v96, v96, v100
	v_add_f32_e32 v97, 1.0, v97
	v_rcp_f32_e32 v97, v97
	s_nop 0
	v_mul_f32_e32 v98, 0xbf1b4598, v97
	v_mul_f32_e32 v98, 0x3fb8aa3b, v98
	v_exp_f32_e32 v98, v98
	s_nop 0
	v_sub_f32_e32 v98, 1.0, v98
	v_cndmask_b32_e32 v97, v97, v98, vcc
	v_add_f32_e32 v98, v99, v203
	v_mul_f32_e32 v98, 0xbfb8aa3b, v98
	v_exp_f32_e32 v98, v98
	s_nop 0
	v_add_f32_e32 v98, 1.0, v98
	v_rcp_f32_e32 v98, v98
	s_nop 0
	v_mul_f32_e32 v99, 0xbf1b4598, v98
	v_mul_f32_e32 v99, 0x3fb8aa3b, v99
	v_exp_f32_e32 v99, v99
	s_nop 0
	v_sub_f32_e32 v99, 1.0, v99
	v_cndmask_b32_e32 v98, v98, v99, vcc
	v_cvt_pk_f16_f32 v97, v97, v98
	global_store_dwordx2 v[108:109], v[96:97], off offset:96
	v_or_b32_e32 v96, 32, v132
	v_ashrrev_i32_e32 v97, 31, v96
	v_lshlrev_b64 v[96:97], 11, v[96:97]
	v_lshl_add_u64 v[100:101], s[6:7], 0, v[96:97]
	v_add_f32_e32 v92, v92, v188
	v_mul_f32_e32 v92, 0xbfb8aa3b, v92
	v_exp_f32_e32 v92, v92
	s_nop 0
	v_add_f32_e32 v92, 1.0, v92
	v_rcp_f32_e32 v92, v92
	s_nop 0
	v_mul_f32_e32 v96, 0xbf1b4598, v92
	v_mul_f32_e32 v96, 0x3fb8aa3b, v96
	v_exp_f32_e32 v96, v96
	s_nop 0
	v_sub_f32_e32 v96, 1.0, v96
	v_cndmask_b32_e32 v96, v92, v96, vcc
	v_add_f32_e32 v92, v93, v189
	v_mul_f32_e32 v92, 0xbfb8aa3b, v92
	v_exp_f32_e32 v92, v92
	s_nop 0
	v_add_f32_e32 v92, 1.0, v92
	v_rcp_f32_e32 v92, v92
	s_nop 0
	v_mul_f32_e32 v93, 0xbf1b4598, v92
	v_mul_f32_e32 v93, 0x3fb8aa3b, v93
	v_exp_f32_e32 v93, v93
	s_nop 0
	v_sub_f32_e32 v93, 1.0, v93
	v_cndmask_b32_e32 v97, v92, v93, vcc
	v_add_f32_e32 v92, v94, v190
	v_mul_f32_e32 v92, 0xbfb8aa3b, v92
	v_exp_f32_e32 v92, v92
	s_nop 0
	v_add_f32_e32 v92, 1.0, v92
	v_rcp_f32_e32 v92, v92
	s_nop 0
	v_mul_f32_e32 v93, 0xbf1b4598, v92
	v_mul_f32_e32 v93, 0x3fb8aa3b, v93
	v_exp_f32_e32 v93, v93
	s_nop 0
	v_sub_f32_e32 v93, 1.0, v93
	v_cndmask_b32_e32 v94, v92, v93, vcc
	v_add_f32_e32 v92, v95, v191
	v_mul_f32_e32 v92, 0xbfb8aa3b, v92
	v_exp_f32_e32 v92, v92
	s_nop 0
	v_add_f32_e32 v92, 1.0, v92
	v_rcp_f32_e32 v92, v92
	s_nop 0
	v_mul_f32_e32 v93, 0xbf1b4598, v92
	v_mul_f32_e32 v93, 0x3fb8aa3b, v93
	v_exp_f32_e32 v93, v93
	s_nop 0
	v_sub_f32_e32 v93, 1.0, v93
	v_cndmask_b32_e32 v95, v92, v93, vcc
	v_lshl_add_u64 v[92:93], v[100:101], 0, v[152:153]
	v_cvt_pk_f16_f32 v95, v94, v95
	v_cvt_pk_f16_f32 v94, v96, v97
	global_store_dwordx2 v[92:93], v[94:95], off
	v_add_f32_e32 v88, v88, v192
	v_mul_f32_e32 v88, 0xbfb8aa3b, v88
	v_exp_f32_e32 v88, v88
	v_add_f32_e32 v89, v89, v193
	v_mul_f32_e32 v89, 0xbfb8aa3b, v89
	v_exp_f32_e32 v89, v89
	v_add_f32_e32 v88, 1.0, v88
	v_rcp_f32_e32 v88, v88
	v_add_f32_e32 v89, 1.0, v89
	v_rcp_f32_e32 v89, v89
	v_mul_f32_e32 v94, 0xbf1b4598, v88
	v_mul_f32_e32 v94, 0x3fb8aa3b, v94
	v_exp_f32_e32 v94, v94
	s_nop 0
	v_sub_f32_e32 v94, 1.0, v94
	v_cndmask_b32_e32 v88, v88, v94, vcc
	v_mul_f32_e32 v94, 0xbf1b4598, v89
	v_mul_f32_e32 v94, 0x3fb8aa3b, v94
	v_exp_f32_e32 v94, v94
	s_nop 0
	v_sub_f32_e32 v94, 1.0, v94
	v_cndmask_b32_e32 v94, v89, v94, vcc
	v_add_f32_e32 v89, v90, v194
	v_mul_f32_e32 v89, 0xbfb8aa3b, v89
	v_exp_f32_e32 v89, v89
	v_cvt_pk_f16_f32 v88, v88, v94
	v_add_f32_e32 v89, 1.0, v89
	v_rcp_f32_e32 v89, v89
	s_nop 0
	v_mul_f32_e32 v90, 0xbf1b4598, v89
	v_mul_f32_e32 v90, 0x3fb8aa3b, v90
	v_exp_f32_e32 v90, v90
	s_nop 0
	v_sub_f32_e32 v90, 1.0, v90
	v_cndmask_b32_e32 v89, v89, v90, vcc
	v_add_f32_e32 v90, v91, v195
	v_mul_f32_e32 v90, 0xbfb8aa3b, v90
	v_exp_f32_e32 v90, v90
	s_nop 0
	v_add_f32_e32 v90, 1.0, v90
	v_rcp_f32_e32 v90, v90
	s_nop 0
	v_mul_f32_e32 v91, 0xbf1b4598, v90
	v_mul_f32_e32 v91, 0x3fb8aa3b, v91
	v_exp_f32_e32 v91, v91
	s_nop 0
	v_sub_f32_e32 v91, 1.0, v91
	v_cndmask_b32_e32 v90, v90, v91, vcc
	v_cvt_pk_f16_f32 v89, v89, v90
	global_store_dwordx2 v[92:93], v[88:89], off offset:32
	v_add_f32_e32 v84, v84, v196
	v_mul_f32_e32 v84, 0xbfb8aa3b, v84
	v_exp_f32_e32 v84, v84
	v_add_f32_e32 v85, v85, v197
	v_mul_f32_e32 v85, 0xbfb8aa3b, v85
	v_exp_f32_e32 v85, v85
	v_add_f32_e32 v84, 1.0, v84
	v_rcp_f32_e32 v84, v84
	v_add_f32_e32 v85, 1.0, v85
	v_rcp_f32_e32 v85, v85
	v_mul_f32_e32 v88, 0xbf1b4598, v84
	v_mul_f32_e32 v88, 0x3fb8aa3b, v88
	v_exp_f32_e32 v88, v88
	s_nop 0
	v_sub_f32_e32 v88, 1.0, v88
	v_cndmask_b32_e32 v84, v84, v88, vcc
	v_mul_f32_e32 v88, 0xbf1b4598, v85
	v_mul_f32_e32 v88, 0x3fb8aa3b, v88
	v_exp_f32_e32 v88, v88
	s_nop 0
	v_sub_f32_e32 v88, 1.0, v88
	v_cndmask_b32_e32 v88, v85, v88, vcc
	v_add_f32_e32 v85, v86, v198
	v_mul_f32_e32 v85, 0xbfb8aa3b, v85
	v_exp_f32_e32 v85, v85
	v_cvt_pk_f16_f32 v84, v84, v88
	v_add_f32_e32 v85, 1.0, v85
	v_rcp_f32_e32 v85, v85
	s_nop 0
	v_mul_f32_e32 v86, 0xbf1b4598, v85
	v_mul_f32_e32 v86, 0x3fb8aa3b, v86
	v_exp_f32_e32 v86, v86
	s_nop 0
	v_sub_f32_e32 v86, 1.0, v86
	v_cndmask_b32_e32 v85, v85, v86, vcc
	v_add_f32_e32 v86, v87, v199
	v_mul_f32_e32 v86, 0xbfb8aa3b, v86
	v_exp_f32_e32 v86, v86
	s_nop 0
	v_add_f32_e32 v86, 1.0, v86
	v_rcp_f32_e32 v86, v86
	s_nop 0
	v_mul_f32_e32 v87, 0xbf1b4598, v86
	v_mul_f32_e32 v87, 0x3fb8aa3b, v87
	v_exp_f32_e32 v87, v87
	s_nop 0
	v_sub_f32_e32 v87, 1.0, v87
	v_cndmask_b32_e32 v86, v86, v87, vcc
	v_cvt_pk_f16_f32 v85, v85, v86
	global_store_dwordx2 v[92:93], v[84:85], off offset:64
	v_add_f32_e32 v80, v80, v200
	v_mul_f32_e32 v80, 0xbfb8aa3b, v80
	v_exp_f32_e32 v80, v80
	v_add_f32_e32 v81, v81, v201
	v_mul_f32_e32 v81, 0xbfb8aa3b, v81
	v_exp_f32_e32 v81, v81
	v_add_f32_e32 v80, 1.0, v80
	v_rcp_f32_e32 v80, v80
	v_add_f32_e32 v81, 1.0, v81
	v_rcp_f32_e32 v81, v81
	v_mul_f32_e32 v84, 0xbf1b4598, v80
	v_mul_f32_e32 v84, 0x3fb8aa3b, v84
	v_exp_f32_e32 v84, v84
	s_nop 0
	v_sub_f32_e32 v84, 1.0, v84
	v_cndmask_b32_e32 v80, v80, v84, vcc
	v_mul_f32_e32 v84, 0xbf1b4598, v81
	v_mul_f32_e32 v84, 0x3fb8aa3b, v84
	v_exp_f32_e32 v84, v84
	s_nop 0
	v_sub_f32_e32 v84, 1.0, v84
	v_cndmask_b32_e32 v84, v81, v84, vcc
	v_add_f32_e32 v81, v82, v202
	v_mul_f32_e32 v81, 0xbfb8aa3b, v81
	v_exp_f32_e32 v81, v81
	v_cvt_pk_f16_f32 v80, v80, v84
	v_add_f32_e32 v81, 1.0, v81
	v_rcp_f32_e32 v81, v81
	s_nop 0
	v_mul_f32_e32 v82, 0xbf1b4598, v81
	v_mul_f32_e32 v82, 0x3fb8aa3b, v82
	v_exp_f32_e32 v82, v82
	s_nop 0
	v_sub_f32_e32 v82, 1.0, v82
	v_cndmask_b32_e32 v81, v81, v82, vcc
	v_add_f32_e32 v82, v83, v203
	v_mul_f32_e32 v82, 0xbfb8aa3b, v82
	v_exp_f32_e32 v82, v82
	s_nop 0
	v_add_f32_e32 v82, 1.0, v82
	v_rcp_f32_e32 v82, v82
	s_nop 0
	v_mul_f32_e32 v83, 0xbf1b4598, v82
	v_mul_f32_e32 v83, 0x3fb8aa3b, v83
	v_exp_f32_e32 v83, v83
	s_nop 0
	v_sub_f32_e32 v83, 1.0, v83
	v_cndmask_b32_e32 v82, v82, v83, vcc
	v_cvt_pk_f16_f32 v81, v81, v82
	global_store_dwordx2 v[92:93], v[80:81], off offset:96
	v_or_b32_e32 v80, 48, v132
	v_ashrrev_i32_e32 v81, 31, v80
	v_lshlrev_b64 v[80:81], 11, v[80:81]
	v_lshl_add_u64 v[84:85], s[6:7], 0, v[80:81]
	v_add_f32_e32 v76, v76, v188
	v_mul_f32_e32 v76, 0xbfb8aa3b, v76
	v_exp_f32_e32 v76, v76
	s_nop 0
	v_add_f32_e32 v76, 1.0, v76
	v_rcp_f32_e32 v76, v76
	s_nop 0
	v_mul_f32_e32 v80, 0xbf1b4598, v76
	v_mul_f32_e32 v80, 0x3fb8aa3b, v80
	v_exp_f32_e32 v80, v80
	s_nop 0
	v_sub_f32_e32 v80, 1.0, v80
	v_cndmask_b32_e32 v80, v76, v80, vcc
	v_add_f32_e32 v76, v77, v189
	v_mul_f32_e32 v76, 0xbfb8aa3b, v76
	v_exp_f32_e32 v76, v76
	s_nop 0
	v_add_f32_e32 v76, 1.0, v76
	v_rcp_f32_e32 v76, v76
	s_nop 0
	v_mul_f32_e32 v77, 0xbf1b4598, v76
	v_mul_f32_e32 v77, 0x3fb8aa3b, v77
	v_exp_f32_e32 v77, v77
	s_nop 0
	v_sub_f32_e32 v77, 1.0, v77
	v_cndmask_b32_e32 v81, v76, v77, vcc
	v_add_f32_e32 v76, v78, v190
	v_mul_f32_e32 v76, 0xbfb8aa3b, v76
	v_exp_f32_e32 v76, v76
	s_nop 0
	v_add_f32_e32 v76, 1.0, v76
	v_rcp_f32_e32 v76, v76
	s_nop 0
	v_mul_f32_e32 v77, 0xbf1b4598, v76
	v_mul_f32_e32 v77, 0x3fb8aa3b, v77
	v_exp_f32_e32 v77, v77
	s_nop 0
	v_sub_f32_e32 v77, 1.0, v77
	v_cndmask_b32_e32 v78, v76, v77, vcc
	v_add_f32_e32 v76, v79, v191
	v_mul_f32_e32 v76, 0xbfb8aa3b, v76
	v_exp_f32_e32 v76, v76
	s_nop 0
	v_add_f32_e32 v76, 1.0, v76
	v_rcp_f32_e32 v76, v76
	s_nop 0
	v_mul_f32_e32 v77, 0xbf1b4598, v76
	v_mul_f32_e32 v77, 0x3fb8aa3b, v77
	v_exp_f32_e32 v77, v77
	s_nop 0
	v_sub_f32_e32 v77, 1.0, v77
	v_cndmask_b32_e32 v79, v76, v77, vcc
	v_lshl_add_u64 v[76:77], v[84:85], 0, v[152:153]
	v_cvt_pk_f16_f32 v79, v78, v79
	v_cvt_pk_f16_f32 v78, v80, v81
	global_store_dwordx2 v[76:77], v[78:79], off
	v_add_f32_e32 v72, v72, v192
	v_mul_f32_e32 v72, 0xbfb8aa3b, v72
	v_exp_f32_e32 v72, v72
	v_add_f32_e32 v73, v73, v193
	v_mul_f32_e32 v73, 0xbfb8aa3b, v73
	v_exp_f32_e32 v73, v73
	v_add_f32_e32 v72, 1.0, v72
	v_rcp_f32_e32 v72, v72
	v_add_f32_e32 v73, 1.0, v73
	v_rcp_f32_e32 v73, v73
	v_mul_f32_e32 v78, 0xbf1b4598, v72
	v_mul_f32_e32 v78, 0x3fb8aa3b, v78
	v_exp_f32_e32 v78, v78
	s_nop 0
	v_sub_f32_e32 v78, 1.0, v78
	v_cndmask_b32_e32 v72, v72, v78, vcc
	v_mul_f32_e32 v78, 0xbf1b4598, v73
	v_mul_f32_e32 v78, 0x3fb8aa3b, v78
	v_exp_f32_e32 v78, v78
	s_nop 0
	v_sub_f32_e32 v78, 1.0, v78
	v_cndmask_b32_e32 v78, v73, v78, vcc
	v_add_f32_e32 v73, v74, v194
	v_mul_f32_e32 v73, 0xbfb8aa3b, v73
	v_exp_f32_e32 v73, v73
	v_cvt_pk_f16_f32 v72, v72, v78
	v_add_f32_e32 v73, 1.0, v73
	v_rcp_f32_e32 v73, v73
	s_nop 0
	v_mul_f32_e32 v74, 0xbf1b4598, v73
	v_mul_f32_e32 v74, 0x3fb8aa3b, v74
	v_exp_f32_e32 v74, v74
	s_nop 0
	v_sub_f32_e32 v74, 1.0, v74
	v_cndmask_b32_e32 v73, v73, v74, vcc
	v_add_f32_e32 v74, v75, v195
	v_mul_f32_e32 v74, 0xbfb8aa3b, v74
	v_exp_f32_e32 v74, v74
	s_nop 0
	v_add_f32_e32 v74, 1.0, v74
	v_rcp_f32_e32 v74, v74
	s_nop 0
	v_mul_f32_e32 v75, 0xbf1b4598, v74
	v_mul_f32_e32 v75, 0x3fb8aa3b, v75
	v_exp_f32_e32 v75, v75
	s_nop 0
	v_sub_f32_e32 v75, 1.0, v75
	v_cndmask_b32_e32 v74, v74, v75, vcc
	v_cvt_pk_f16_f32 v73, v73, v74
	global_store_dwordx2 v[76:77], v[72:73], off offset:32
	v_add_f32_e32 v68, v68, v196
	v_mul_f32_e32 v68, 0xbfb8aa3b, v68
	v_exp_f32_e32 v68, v68
	v_add_f32_e32 v69, v69, v197
	v_mul_f32_e32 v69, 0xbfb8aa3b, v69
	v_exp_f32_e32 v69, v69
	v_add_f32_e32 v68, 1.0, v68
	v_rcp_f32_e32 v68, v68
	v_add_f32_e32 v69, 1.0, v69
	v_rcp_f32_e32 v69, v69
	v_mul_f32_e32 v72, 0xbf1b4598, v68
	v_mul_f32_e32 v72, 0x3fb8aa3b, v72
	v_exp_f32_e32 v72, v72
	s_nop 0
	v_sub_f32_e32 v72, 1.0, v72
	v_cndmask_b32_e32 v68, v68, v72, vcc
	v_mul_f32_e32 v72, 0xbf1b4598, v69
	v_mul_f32_e32 v72, 0x3fb8aa3b, v72
	v_exp_f32_e32 v72, v72
	s_nop 0
	v_sub_f32_e32 v72, 1.0, v72
	v_cndmask_b32_e32 v72, v69, v72, vcc
	v_add_f32_e32 v69, v70, v198
	v_mul_f32_e32 v69, 0xbfb8aa3b, v69
	v_exp_f32_e32 v69, v69
	v_cvt_pk_f16_f32 v68, v68, v72
	v_add_f32_e32 v69, 1.0, v69
	v_rcp_f32_e32 v69, v69
	s_nop 0
	v_mul_f32_e32 v70, 0xbf1b4598, v69
	v_mul_f32_e32 v70, 0x3fb8aa3b, v70
	v_exp_f32_e32 v70, v70
	s_nop 0
	v_sub_f32_e32 v70, 1.0, v70
	v_cndmask_b32_e32 v69, v69, v70, vcc
	v_add_f32_e32 v70, v71, v199
	v_mul_f32_e32 v70, 0xbfb8aa3b, v70
	v_exp_f32_e32 v70, v70
	s_nop 0
	v_add_f32_e32 v70, 1.0, v70
	v_rcp_f32_e32 v70, v70
	s_nop 0
	v_mul_f32_e32 v71, 0xbf1b4598, v70
	v_mul_f32_e32 v71, 0x3fb8aa3b, v71
	v_exp_f32_e32 v71, v71
	s_nop 0
	v_sub_f32_e32 v71, 1.0, v71
	v_cndmask_b32_e32 v70, v70, v71, vcc
	v_cvt_pk_f16_f32 v69, v69, v70
	global_store_dwordx2 v[76:77], v[68:69], off offset:64
	s_mov_b32 s4, s13
	v_add_f32_e32 v64, v64, v200
	v_mul_f32_e32 v64, 0xbfb8aa3b, v64
	v_exp_f32_e32 v64, v64
	v_add_f32_e32 v65, v65, v201
	v_mul_f32_e32 v65, 0xbfb8aa3b, v65
	v_exp_f32_e32 v65, v65
	v_add_f32_e32 v64, 1.0, v64
	v_rcp_f32_e32 v64, v64
	v_add_f32_e32 v65, 1.0, v65
	v_rcp_f32_e32 v65, v65
	v_mul_f32_e32 v68, 0xbf1b4598, v64
	v_mul_f32_e32 v68, 0x3fb8aa3b, v68
	v_exp_f32_e32 v68, v68
	s_nop 0
	v_sub_f32_e32 v68, 1.0, v68
	v_cndmask_b32_e32 v64, v64, v68, vcc
	v_mul_f32_e32 v68, 0xbf1b4598, v65
	v_mul_f32_e32 v68, 0x3fb8aa3b, v68
	v_exp_f32_e32 v68, v68
	s_nop 0
	v_sub_f32_e32 v68, 1.0, v68
	v_cndmask_b32_e32 v68, v65, v68, vcc
	v_add_f32_e32 v65, v66, v202
	v_mul_f32_e32 v65, 0xbfb8aa3b, v65
	v_exp_f32_e32 v65, v65
	v_cvt_pk_f16_f32 v64, v64, v68
	v_add_f32_e32 v65, 1.0, v65
	v_rcp_f32_e32 v65, v65
	s_nop 0
	v_mul_f32_e32 v66, 0xbf1b4598, v65
	v_mul_f32_e32 v66, 0x3fb8aa3b, v66
	v_exp_f32_e32 v66, v66
	s_nop 0
	v_sub_f32_e32 v66, 1.0, v66
	v_cndmask_b32_e32 v65, v65, v66, vcc
	v_add_f32_e32 v66, v67, v203
	v_mul_f32_e32 v66, 0xbfb8aa3b, v66
	v_exp_f32_e32 v66, v66
	s_nop 0
	v_add_f32_e32 v66, 1.0, v66
	v_rcp_f32_e32 v66, v66
	s_nop 0
	v_mul_f32_e32 v67, 0xbf1b4598, v66
	v_mul_f32_e32 v67, 0x3fb8aa3b, v67
	v_exp_f32_e32 v67, v67
	s_nop 0
	v_sub_f32_e32 v67, 1.0, v67
	v_cndmask_b32_e32 v66, v66, v67, vcc
	v_cvt_pk_f16_f32 v65, v65, v66
	s_andn2_b64 vcc, exec, s[0:1]
	global_store_dwordx2 v[76:77], v[64:65], off offset:96
	s_cbranch_vccz .LBB0_2048
.LBB0_2046:
	s_waitcnt vmcnt(23)
	v_mfma_f32_16x16x32_bf16 v[64:67], v[32:35], v[0:3], 0
	v_readlane_b32 s0, v254, 22
	s_add_i32 s13, s4, s0
	v_readlane_b32 s1, v254, 23
	s_waitcnt vmcnt(21)
	v_mfma_f32_16x16x32_bf16 v[68:71], v[40:43], v[0:3], 0
	s_cmpk_gt_i32 s13, 0x41ff
	s_cselect_b64 s[0:1], -1, 0
	s_and_b64 vcc, exec, s[0:1]
	s_waitcnt vmcnt(19)
	v_mfma_f32_16x16x32_bf16 v[72:75], v[48:51], v[0:3], 0
	s_waitcnt vmcnt(17)
	v_mfma_f32_16x16x32_bf16 v[76:79], v[56:59], v[0:3], 0
	v_mfma_f32_16x16x32_bf16 v[80:83], v[32:35], v[8:11], 0
	v_mfma_f32_16x16x32_bf16 v[84:87], v[40:43], v[8:11], 0
	v_mfma_f32_16x16x32_bf16 v[88:91], v[48:51], v[8:11], 0
	v_mfma_f32_16x16x32_bf16 v[92:95], v[56:59], v[8:11], 0
	v_mfma_f32_16x16x32_bf16 v[138:141], v[32:35], v[16:19], 0
	v_mfma_f32_16x16x32_bf16 v[142:145], v[40:43], v[16:19], 0
	v_mfma_f32_16x16x32_bf16 v[146:149], v[48:51], v[16:19], 0
	v_mfma_f32_16x16x32_bf16 v[166:169], v[56:59], v[16:19], 0
	v_mfma_f32_16x16x32_bf16 v[170:173], v[32:35], v[24:27], 0
	v_mfma_f32_16x16x32_bf16 v[174:177], v[40:43], v[24:27], 0
	v_mfma_f32_16x16x32_bf16 v[178:181], v[48:51], v[24:27], 0
	v_mfma_f32_16x16x32_bf16 v[182:185], v[56:59], v[24:27], 0
	v_mfma_f32_16x16x32_bf16 v[124:127], v[36:39], v[4:7], v[64:67]
	v_mfma_f32_16x16x32_bf16 v[120:123], v[44:47], v[4:7], v[68:71]
	v_mfma_f32_16x16x32_bf16 v[116:119], v[52:55], v[4:7], v[72:75]
	s_waitcnt vmcnt(16)
	v_mfma_f32_16x16x32_bf16 v[112:115], v[60:63], v[4:7], v[76:79]
	v_mfma_f32_16x16x32_bf16 v[108:111], v[36:39], v[12:15], v[80:83]
	v_mfma_f32_16x16x32_bf16 v[104:107], v[44:47], v[12:15], v[84:87]
	v_mfma_f32_16x16x32_bf16 v[100:103], v[52:55], v[12:15], v[88:91]
	v_mfma_f32_16x16x32_bf16 v[96:99], v[60:63], v[12:15], v[92:95]
	v_mfma_f32_16x16x32_bf16 v[92:95], v[36:39], v[20:23], v[138:141]
	v_mfma_f32_16x16x32_bf16 v[88:91], v[44:47], v[20:23], v[142:145]
	v_mfma_f32_16x16x32_bf16 v[84:87], v[52:55], v[20:23], v[146:149]
	v_mfma_f32_16x16x32_bf16 v[80:83], v[60:63], v[20:23], v[166:169]
	v_mfma_f32_16x16x32_bf16 v[76:79], v[36:39], v[28:31], v[170:173]
	v_mfma_f32_16x16x32_bf16 v[72:75], v[44:47], v[28:31], v[174:177]
	v_mfma_f32_16x16x32_bf16 v[68:71], v[52:55], v[28:31], v[178:181]
	v_mfma_f32_16x16x32_bf16 v[64:67], v[60:63], v[28:31], v[182:185]
	s_ashr_i32 s5, s4, 31
	s_lshr_b32 s5, s5, 26
	s_add_i32 s5, s4, s5
	s_andn2_b32 s5, s5, 63
	s_sub_i32 s14, s4, s5
	s_lshr_b32 s14, s14, 4
	s_and_b32 s5, s10, 0x3c0
	v_or_b32_e32 v204, s5, v135
	v_lshlrev_b32_e32 v204, 2, v204
	s_cmp_lt_i32 s14, 2
	s_cselect_b32 s6, s2, s8
	s_cselect_b32 s7, s3, s9
	s_add_u32 s6, s6, s12
	s_addc_u32 s7, s7, 0
	s_lshl_b32 s5, s14, 12
	s_and_b32 s5, s5, 0x1000
	s_add_u32 s6, s6, s5
	s_addc_u32 s7, s7, 0
	global_load_dwordx4 v[188:191], v204, s[6:7]
	global_load_dwordx4 v[192:195], v204, s[6:7] offset:64
	global_load_dwordx4 v[196:199], v204, s[6:7] offset:128
	global_load_dwordx4 v[200:203], v204, s[6:7] offset:192
	s_cbranch_vccnz .Llr_nopf
	s_ashr_i32 s5, s13, 31
	s_lshr_b32 s5, s5, 26
	s_add_i32 s5, s13, s5
	s_and_b32 s7, s5, 0xffffffc0
	s_sub_i32 s6, s13, s7
	s_lshr_b32 s6, s6, 4
	s_bfe_i32 s14, s6, 0x80000
	s_bfe_u32 s14, s14, 0x2000d
	s_add_i32 s14, s6, s14
	s_and_b32 s14, s14, 0xfc
	s_sub_i32 s6, s6, s14
	s_lshl_b32 s5, s5, 6
	s_sext_i32_i8 s6, s6
	v_add_u32_e32 v2, s10, v136
	s_and_b32 s5, s5, 0xfffff000
	s_lshl_b32 s6, s6, 6
	v_subrev_u32_e32 v2, s5, v2
	v_or_b32_e32 v8, s7, v134
	s_ashr_i32 s7, s6, 31
	v_ashrrev_i32_e32 v3, 31, v2
	v_lshl_add_u64 v[0:1], s[6:7], 1, v[130:131]
	v_lshlrev_b64 v[4:5], 7, v[2:3]
	v_or_b32_e32 v3, 16, v8
	v_mad_i64_i32 v[12:13], s[6:7], v3, s95, v[0:1]
	v_or_b32_e32 v3, 32, v8
	v_mad_i64_i32 v[20:21], s[6:7], v3, s95, v[0:1]
	v_or_b32_e32 v3, 48, v8
	v_mad_i64_i32 v[6:7], s[6:7], v8, s95, v[0:1]
	v_mad_i64_i32 v[28:29], s[6:7], v3, s95, v[0:1]
	v_add_u32_e32 v0, 16, v2
	v_ashrrev_i32_e32 v1, 31, v0
	v_lshlrev_b64 v[0:1], 7, v[0:1]
	v_lshl_add_u64 v[44:45], v[128:129], 0, v[0:1]
	v_add_u32_e32 v0, 32, v2
	v_ashrrev_i32_e32 v1, 31, v0
	v_lshlrev_b64 v[0:1], 7, v[0:1]
	v_lshl_add_u64 v[52:53], v[128:129], 0, v[0:1]
	v_add_u32_e32 v0, 48, v2
	v_ashrrev_i32_e32 v1, 31, v0
	v_lshlrev_b64 v[0:1], 7, v[0:1]
	v_lshl_add_u64 v[36:37], v[128:129], 0, v[4:5]
	v_lshl_add_u64 v[60:61], v[128:129], 0, v[0:1]
	global_load_dwordx4 v[0:3], v[6:7], off
	s_nop 0
	global_load_dwordx4 v[4:7], v[6:7], off offset:64
	s_nop 0
	global_load_dwordx4 v[8:11], v[12:13], off
	s_nop 0
	global_load_dwordx4 v[12:15], v[12:13], off offset:64
	s_nop 0
	global_load_dwordx4 v[16:19], v[20:21], off
	s_nop 0
	global_load_dwordx4 v[20:23], v[20:21], off offset:64
	s_nop 0
	global_load_dwordx4 v[24:27], v[28:29], off
	s_nop 0
	global_load_dwordx4 v[28:31], v[28:29], off offset:64
	s_nop 0
	global_load_dwordx4 v[32:35], v[36:37], off
	s_nop 0
	global_load_dwordx4 v[36:39], v[36:37], off offset:64
	s_nop 0
	global_load_dwordx4 v[40:43], v[44:45], off
	s_nop 0
	global_load_dwordx4 v[44:47], v[44:45], off offset:64
	s_nop 0
	global_load_dwordx4 v[48:51], v[52:53], off
	s_nop 0
	global_load_dwordx4 v[52:55], v[52:53], off offset:64
	s_nop 0
	global_load_dwordx4 v[56:59], v[60:61], off
	s_nop 0
	global_load_dwordx4 v[60:63], v[60:61], off offset:64
	s_waitcnt vmcnt(16)
	s_branch .LBB0_2045
.Llr_nopf:
	s_waitcnt vmcnt(0)
	s_branch .LBB0_2045
